# P1 epilogue: hoist per-row rstd loads, drop per-row vmcnt(0) drains, prefetch rope table one row ahead with counted wait
# speedup vs baseline: 1.0035x; 1.0035x over previous
.LBB0_501:
	s_lshl_b32 s76, s10, 8
	s_add_i32 s76, s76, s97
	v_or_b32_e32 v184, s76, v149
	v_ashrrev_i32_e32 v185, 31, v184
	v_lshl_add_u64 v[0:1], v[184:185], 2, s[26:27]
	global_load_dword v150, v[0:1], off
	global_load_dword v241, v[0:1], off offset:64
	global_load_dword v242, v[0:1], off offset:128
	global_load_dword v243, v[0:1], off offset:192
	global_load_dword v244, v[0:1], off offset:512
	global_load_dword v245, v[0:1], off offset:576
	global_load_dword v246, v[0:1], off offset:640
	global_load_dword v247, v[0:1], off offset:704
	s_xor_b64 s[12:13], s[12:13], -1
	s_xor_b64 s[72:73], s[70:71], -1
	v_lshl_add_u64 v[178:179], s[14:15], 0, v[152:153]
	s_mov_b64 s[10:11], -1
	s_and_b64 vcc, exec, s[12:13]
	s_cbranch_vccz .LBB0_510
	s_and_b64 vcc, exec, s[72:73]
	s_cbranch_vccz .LBB0_507
	s_and_saveexec_b64 s[10:11], s[6:7]
	s_cbranch_execz .LBB0_506
	s_waitcnt vmcnt(0)
	v_mul_f32_e32 v0, v16, v150
	v_mul_f32_e32 v0, 0xbfb8aa3b, v0
	v_mul_f32_e32 v1, v17, v150
	v_exp_f32_e32 v0, v0
	v_mul_f32_e32 v1, 0xbfb8aa3b, v1
	v_exp_f32_e32 v1, v1
	v_mul_f32_e32 v3, v19, v150
	v_add_f32_e32 v0, 1.0, v0
	v_rcp_f32_e32 v2, v0
	v_add_f32_e32 v0, 1.0, v1
	v_mul_f32_e32 v1, v18, v150
	v_mul_f32_e32 v1, 0xbfb8aa3b, v1
	v_exp_f32_e32 v1, v1
	v_mul_f32_e32 v3, 0xbfb8aa3b, v3
	v_exp_f32_e32 v5, v3
	v_rcp_f32_e32 v3, v0
	v_add_f32_e32 v0, 1.0, v1
	v_mul_f32_e32 v1, v20, v150
	v_rcp_f32_e32 v4, v0
	v_add_f32_e32 v0, 1.0, v5
	v_mul_f32_e32 v1, 0xbfb8aa3b, v1
	v_mul_f32_e32 v5, v21, v150
	v_exp_f32_e32 v1, v1
	v_mul_f32_e32 v5, 0xbfb8aa3b, v5
	v_exp_f32_e32 v7, v5
	v_rcp_f32_e32 v5, v0
	v_add_f32_e32 v0, 1.0, v1
	v_mul_f32_e32 v1, v22, v150
	v_rcp_f32_e32 v6, v0
	v_add_f32_e32 v0, 1.0, v7
	v_mul_f32_e32 v1, 0xbfb8aa3b, v1
	v_mul_f32_e32 v7, v23, v150
	v_exp_f32_e32 v1, v1
	v_mul_f32_e32 v7, 0xbfb8aa3b, v7
	v_exp_f32_e32 v9, v7
	v_rcp_f32_e32 v7, v0
	v_add_f32_e32 v0, 1.0, v1
	v_rcp_f32_e32 v8, v0
	v_add_f32_e32 v0, 1.0, v9
	v_rcp_f32_e32 v9, v0
	v_lshlrev_b64 v[0:1], 7, v[184:185]
	v_lshl_add_u64 v[0:1], v[154:155], 0, v[0:1]
	global_store_dwordx4 v[0:1], v[2:5], off
	global_store_dwordx4 v[0:1], v[6:9], off offset:16
	s_and_b64 exec, exec, s[8:9]
	s_cbranch_execz .LBB0_506
	v_mul_f32_e32 v2, v24, v150
	v_mul_f32_e32 v3, v25, v150
	v_mul_f32_e32 v4, v26, v150
	v_mul_f32_e32 v5, v27, v150
	v_mul_f32_e32 v2, 0xbfb8aa3b, v2
	v_mul_f32_e32 v3, 0xbfb8aa3b, v3
	v_mul_f32_e32 v4, 0xbfb8aa3b, v4
	v_mul_f32_e32 v5, 0xbfb8aa3b, v5
	v_mul_f32_e32 v6, v28, v150
	v_mul_f32_e32 v7, v29, v150
	v_mul_f32_e32 v8, v30, v150
	v_mul_f32_e32 v9, v31, v150
	v_exp_f32_e32 v2, v2
	v_exp_f32_e32 v3, v3
	v_exp_f32_e32 v4, v4
	v_exp_f32_e32 v5, v5
	v_mul_f32_e32 v6, 0xbfb8aa3b, v6
	v_mul_f32_e32 v7, 0xbfb8aa3b, v7
	v_mul_f32_e32 v8, 0xbfb8aa3b, v8
	v_mul_f32_e32 v9, 0xbfb8aa3b, v9
	v_exp_f32_e32 v6, v6
	v_exp_f32_e32 v7, v7
	v_exp_f32_e32 v8, v8
	v_exp_f32_e32 v9, v9
	v_add_f32_e32 v2, 1.0, v2
	v_add_f32_e32 v3, 1.0, v3
	v_add_f32_e32 v4, 1.0, v4
	v_add_f32_e32 v5, 1.0, v5
	v_rcp_f32_e32 v2, v2
	v_rcp_f32_e32 v3, v3
	v_rcp_f32_e32 v4, v4
	v_rcp_f32_e32 v5, v5
	v_add_f32_e32 v6, 1.0, v6
	v_add_f32_e32 v7, 1.0, v7
	v_add_f32_e32 v8, 1.0, v8
	v_add_f32_e32 v9, 1.0, v9
	v_rcp_f32_e32 v6, v6
	v_rcp_f32_e32 v7, v7
	v_rcp_f32_e32 v8, v8
	v_rcp_f32_e32 v9, v9
	global_store_dwordx4 v[0:1], v[2:5], off offset:32
	global_store_dwordx4 v[0:1], v[6:9], off offset:48

.LBB0_514:
	s_and_saveexec_b64 s[4:5], s[70:71]
	s_cbranch_execz .LBB0_516
	v_lshlrev_b64 v[16:17], 6, v[184:185]
	v_lshl_add_u64 v[16:17], s[28:29], 0, v[16:17]
	global_load_dwordx4 v[28:31], v[16:17], off offset:48
	global_load_dwordx4 v[196:199], v[16:17], off offset:16
	global_load_dwordx4 v[18:21], v[16:17], off offset:32
	global_load_dwordx4 v[24:27], v[16:17], off
	s_waitcnt vmcnt(0)
	v_pk_mul_f32 v[16:17], v[8:9], v[18:19]
	s_nop 0
	v_pk_fma_f32 v[16:17], v[0:1], v[24:25], v[16:17] neg_lo:[0,0,1] neg_hi:[0,0,1]
	v_pk_mul_f32 v[0:1], v[0:1], v[18:19]
	s_nop 0
	v_pk_fma_f32 v[24:25], v[8:9], v[24:25], v[0:1]
	v_pk_mul_f32 v[0:1], v[10:11], v[20:21]
	s_nop 0
	v_pk_fma_f32 v[18:19], v[2:3], v[26:27], v[0:1] neg_lo:[0,0,1] neg_hi:[0,0,1]
	v_pk_mul_f32 v[0:1], v[2:3], v[20:21]
	v_mul_f32_e32 v2, v6, v30
	v_pk_fma_f32 v[26:27], v[10:11], v[26:27], v[0:1]
	v_pk_mul_f32 v[0:1], v[12:13], v[28:29]
	s_nop 0
	v_pk_fma_f32 v[20:21], v[4:5], v[196:197], v[0:1] neg_lo:[0,0,1] neg_hi:[0,0,1]
	v_pk_mul_f32 v[0:1], v[4:5], v[28:29]
	v_pk_mul_f32 v[4:5], v[14:15], v[30:31]
	v_mov_b32_e32 v30, v199
	v_pk_fma_f32 v[22:23], v[6:7], v[198:199], v[4:5] neg_lo:[0,0,1] neg_hi:[0,0,1]
	v_mov_b32_e32 v6, v15
	v_pk_mul_f32 v[4:5], v[6:7], v[30:31]
	v_pk_fma_f32 v[28:29], v[12:13], v[196:197], v[0:1]
	v_mul_f32_e32 v0, v14, v198
	v_mov_b32_e32 v1, v4
	v_mov_b32_e32 v3, v5
	v_pk_add_f32 v[30:31], v[0:1], v[2:3]
	s_nop 0
	v_mov_b64_e32 v[0:1], v[16:17]
	v_mov_b64_e32 v[2:3], v[18:19]
	v_mov_b64_e32 v[4:5], v[20:21]
	v_mov_b64_e32 v[6:7], v[22:23]
	v_mov_b64_e32 v[8:9], v[24:25]
	v_mov_b64_e32 v[10:11], v[26:27]
	v_mov_b64_e32 v[12:13], v[28:29]
	v_mov_b64_e32 v[14:15], v[30:31]
	v_lshlrev_b64 v[216:217], 6, v[184:185]
	v_lshl_add_u64 v[216:217], s[28:29], 0, v[216:217]
	s_mov_b64 s[98:99], 0x2000
	v_lshl_add_u64 v[218:219], v[216:217], 0, s[98:99]
	global_load_dwordx4 v[208:211], v[216:217], off offset:1072
	global_load_dwordx4 v[212:215], v[216:217], off offset:1040
	global_load_dwordx4 v[204:207], v[216:217], off offset:1056
	global_load_dwordx4 v[200:203], v[216:217], off offset:1024
.LBB0_516:
	s_or_b64 exec, exec, s[4:5]
	v_lshlrev_b32_e32 v16, 7, v184
	v_and_b32_e32 v150, 0x3e780, v16
	v_lshl_add_u64 v[16:17], v[182:183], 0, v[150:151]
	v_cvt_pk_bf16_f32 v0, v0, v1
	v_cvt_pk_bf16_f32 v1, v2, v3
	v_cvt_pk_bf16_f32 v2, v4, v5
	v_cvt_pk_bf16_f32 v3, v6, v7
	v_cvt_pk_bf16_f32 v4, v8, v9
	v_cvt_pk_bf16_f32 v5, v10, v11
	v_cvt_pk_bf16_f32 v6, v12, v13
	v_cvt_pk_bf16_f32 v7, v14, v15
	global_store_dwordx4 v[16:17], v[0:3], off
	global_store_dwordx4 v[16:17], v[4:7], off offset:16
.LBB0_517:
	v_or_b32_e32 v186, 16, v184
	v_ashrrev_i32_e32 v187, 31, v186
	v_lshl_add_u64 v[0:1], v[186:187], 2, s[26:27]
	v_mov_b32_e32 v16, v241
	v_cndmask_b32_e64 v0, 0, 1, s[12:13]
	v_cmp_ne_u32_e64 s[14:15], 1, v0
	v_cndmask_b32_e64 v0, 0, 1, s[72:73]
	s_mov_b64 s[4:5], -1
	s_andn2_b64 vcc, exec, s[12:13]
	v_cmp_ne_u32_e64 s[12:13], 1, v0
	s_cbranch_vccnz .LBB0_526
	s_and_b64 vcc, exec, s[12:13]
	s_cbranch_vccnz .LBB0_523
	s_and_saveexec_b64 s[4:5], s[6:7]
	s_cbranch_execz .LBB0_522
	v_mul_f32_e32 v0, v128, v16
	v_mul_f32_e32 v0, 0xbfb8aa3b, v0
	v_mul_f32_e32 v1, v129, v16
	v_exp_f32_e32 v0, v0
	v_mul_f32_e32 v1, 0xbfb8aa3b, v1
	v_exp_f32_e32 v1, v1
	v_mul_f32_e32 v3, v131, v16
	v_add_f32_e32 v0, 1.0, v0
	v_rcp_f32_e32 v2, v0
	v_add_f32_e32 v0, 1.0, v1
	v_mul_f32_e32 v1, v130, v16
	v_mul_f32_e32 v1, 0xbfb8aa3b, v1
	v_exp_f32_e32 v1, v1
	v_mul_f32_e32 v3, 0xbfb8aa3b, v3
	v_exp_f32_e32 v5, v3
	v_rcp_f32_e32 v3, v0
	v_add_f32_e32 v0, 1.0, v1
	v_mul_f32_e32 v1, v132, v16
	v_rcp_f32_e32 v4, v0
	v_add_f32_e32 v0, 1.0, v5
	v_mul_f32_e32 v1, 0xbfb8aa3b, v1
	v_mul_f32_e32 v5, v133, v16
	v_exp_f32_e32 v1, v1
	v_mul_f32_e32 v5, 0xbfb8aa3b, v5
	v_exp_f32_e32 v7, v5
	v_rcp_f32_e32 v5, v0
	v_add_f32_e32 v0, 1.0, v1
	v_mul_f32_e32 v1, v134, v16
	v_rcp_f32_e32 v6, v0
	v_add_f32_e32 v0, 1.0, v7
	v_mul_f32_e32 v1, 0xbfb8aa3b, v1
	v_mul_f32_e32 v7, v135, v16
	v_exp_f32_e32 v1, v1
	v_mul_f32_e32 v7, 0xbfb8aa3b, v7
	v_exp_f32_e32 v9, v7
	v_rcp_f32_e32 v7, v0
	v_add_f32_e32 v0, 1.0, v1
	v_rcp_f32_e32 v8, v0
	v_add_f32_e32 v0, 1.0, v9
	v_rcp_f32_e32 v9, v0
	v_lshlrev_b64 v[0:1], 7, v[186:187]
	v_lshl_add_u64 v[0:1], v[154:155], 0, v[0:1]
	global_store_dwordx4 v[0:1], v[2:5], off
	global_store_dwordx4 v[0:1], v[6:9], off offset:16
	s_and_b64 exec, exec, s[8:9]
	s_cbranch_execz .LBB0_522
	v_mul_f32_e32 v2, v136, v16
	v_mul_f32_e32 v3, v137, v16
	v_mul_f32_e32 v4, v138, v16
	v_mul_f32_e32 v5, v139, v16
	v_mul_f32_e32 v2, 0xbfb8aa3b, v2
	v_mul_f32_e32 v3, 0xbfb8aa3b, v3
	v_mul_f32_e32 v4, 0xbfb8aa3b, v4
	v_mul_f32_e32 v5, 0xbfb8aa3b, v5
	v_mul_f32_e32 v6, v140, v16
	v_mul_f32_e32 v7, v141, v16
	v_mul_f32_e32 v8, v142, v16
	v_mul_f32_e32 v9, v143, v16
	v_exp_f32_e32 v2, v2
	v_exp_f32_e32 v3, v3
	v_exp_f32_e32 v4, v4
	v_exp_f32_e32 v5, v5
	v_mul_f32_e32 v6, 0xbfb8aa3b, v6
	v_mul_f32_e32 v7, 0xbfb8aa3b, v7
	v_mul_f32_e32 v8, 0xbfb8aa3b, v8
	v_mul_f32_e32 v9, 0xbfb8aa3b, v9
	v_exp_f32_e32 v6, v6
	v_exp_f32_e32 v7, v7
	v_exp_f32_e32 v8, v8
	v_exp_f32_e32 v9, v9
	v_add_f32_e32 v2, 1.0, v2
	v_add_f32_e32 v3, 1.0, v3
	v_add_f32_e32 v4, 1.0, v4
	v_add_f32_e32 v5, 1.0, v5
	v_rcp_f32_e32 v2, v2
	v_rcp_f32_e32 v3, v3
	v_rcp_f32_e32 v4, v4
	v_rcp_f32_e32 v5, v5
	v_add_f32_e32 v6, 1.0, v6
	v_add_f32_e32 v7, 1.0, v7
	v_add_f32_e32 v8, 1.0, v8
	v_add_f32_e32 v9, 1.0, v9
	v_rcp_f32_e32 v6, v6
	v_rcp_f32_e32 v7, v7
	v_rcp_f32_e32 v8, v8
	v_rcp_f32_e32 v9, v9
	global_store_dwordx4 v[0:1], v[2:5], off offset:32
	global_store_dwordx4 v[0:1], v[6:9], off offset:48

.LBB0_523:
	s_andn2_b64 vcc, exec, s[4:5]
	s_cbranch_vccnz .LBB0_525
	v_mul_f32_e32 v3, 0xbfb8aa3b, v16
	v_mul_f32_e32 v0, v128, v3
	v_exp_f32_e32 v0, v0
	v_mul_f32_e32 v1, v129, v3
	v_exp_f32_e32 v1, v1
	v_mul_f32_e32 v2, v130, v3
	v_fmamk_f32 v0, v0, 0x3b808081, v193
	v_rcp_f32_e32 v0, v0
	v_fmamk_f32 v1, v1, 0x3b808081, v193
	v_rcp_f32_e32 v1, v1
	v_exp_f32_e32 v2, v2
	v_cvt_pk_u8_f32 v0, v0, 0, 0
	v_mul_f32_e32 v4, v132, v3
	v_cvt_pk_u8_f32 v0, v1, 1, v0
	v_fmamk_f32 v1, v2, 0x3b808081, v193
	v_mul_f32_e32 v2, v131, v3
	v_exp_f32_e32 v4, v4
	v_exp_f32_e32 v2, v2
	v_rcp_f32_e32 v1, v1
	v_mul_f32_e32 v5, v133, v3
	v_fmamk_f32 v4, v4, 0x3b808081, v193
	v_fmamk_f32 v2, v2, 0x3b808081, v193
	v_rcp_f32_e32 v4, v4
	v_rcp_f32_e32 v2, v2
	v_exp_f32_e32 v5, v5
	v_cvt_pk_u8_f32 v0, v1, 2, v0
	v_cvt_pk_u8_f32 v1, v4, 0, 0
	v_mul_f32_e32 v4, v134, v3
	v_cvt_pk_u8_f32 v0, v2, 3, v0
	v_fmamk_f32 v2, v5, 0x3b808081, v193
	v_exp_f32_e32 v4, v4
	v_mul_f32_e32 v5, v135, v3
	v_exp_f32_e32 v5, v5
	v_rcp_f32_e32 v2, v2
	v_fmamk_f32 v4, v4, 0x3b808081, v193
	v_rcp_f32_e32 v4, v4
	v_fmamk_f32 v5, v5, 0x3b808081, v193
	v_rcp_f32_e32 v5, v5
	v_mul_f32_e32 v6, v136, v3
	v_cvt_pk_u8_f32 v1, v2, 1, v1
	v_exp_f32_e32 v6, v6
	v_cvt_pk_u8_f32 v1, v4, 2, v1
	v_mul_f32_e32 v4, v137, v3
	v_cvt_pk_u8_f32 v1, v5, 3, v1
	v_exp_f32_e32 v4, v4
	v_mul_f32_e32 v5, v138, v3
	v_exp_f32_e32 v5, v5
	v_fmamk_f32 v2, v6, 0x3b808081, v193
	v_rcp_f32_e32 v2, v2
	v_fmamk_f32 v4, v4, 0x3b808081, v193
	v_rcp_f32_e32 v4, v4
	v_fmamk_f32 v5, v5, 0x3b808081, v193
	v_mul_f32_e32 v6, v139, v3
	v_rcp_f32_e32 v5, v5
	v_exp_f32_e32 v6, v6
	v_cvt_pk_u8_f32 v2, v2, 0, 0
	v_cvt_pk_u8_f32 v2, v4, 1, v2
	v_cvt_pk_u8_f32 v2, v5, 2, v2
	v_fmamk_f32 v4, v6, 0x3b808081, v193
	v_mul_f32_e32 v5, v140, v3
	v_mul_f32_e32 v6, v141, v3
	v_rcp_f32_e32 v4, v4
	v_exp_f32_e32 v5, v5
	v_exp_f32_e32 v6, v6
	v_cvt_pk_u8_f32 v2, v4, 3, v2
	v_fmamk_f32 v4, v5, 0x3b808081, v193
	v_fmamk_f32 v5, v6, 0x3b808081, v193
	v_mul_f32_e32 v6, v142, v3
	v_exp_f32_e32 v6, v6
	v_mul_f32_e32 v3, v143, v3
	v_exp_f32_e32 v3, v3
	v_rcp_f32_e32 v4, v4
	v_rcp_f32_e32 v5, v5
	v_fmamk_f32 v6, v6, 0x3b808081, v193
	v_rcp_f32_e32 v6, v6
	v_fmamk_f32 v3, v3, 0x3b808081, v193
	v_rcp_f32_e32 v3, v3
	v_cvt_pk_u8_f32 v4, v4, 0, 0
	v_cvt_pk_u8_f32 v4, v5, 1, v4
	v_cvt_pk_u8_f32 v4, v6, 2, v4
	v_cvt_pk_u8_f32 v3, v3, 3, v4
	v_lshlrev_b64 v[4:5], 10, v[186:187]
	v_lshl_add_u64 v[4:5], v[178:179], 0, v[4:5]
	global_store_dwordx4 v[4:5], v[0:3], off

.LBB0_526:
	s_andn2_b64 vcc, exec, s[4:5]
	s_cbranch_vccnz .LBB0_533
	s_and_b64 vcc, exec, s[10:11]
	s_cbranch_vccnz .LBB0_633
	v_mul_f32_e32 v4, v129, v129
	v_fmac_f32_e32 v4, v128, v128
	v_fmac_f32_e32 v4, v130, v130
	v_fmac_f32_e32 v4, v131, v131
	v_fmac_f32_e32 v4, v132, v132
	v_fmac_f32_e32 v4, v133, v133
	v_fmac_f32_e32 v4, v134, v134
	v_fmac_f32_e32 v4, v135, v135
	v_pk_mul_f32 v[2:3], v[136:137], v[136:137]
	v_pk_mul_f32 v[0:1], v[138:139], v[138:139]
	v_add_f32_e32 v2, v2, v4
	v_add_f32_e32 v2, v3, v2
	v_add_f32_e32 v0, v0, v2
	v_add_f32_e32 v4, v1, v0
	v_pk_mul_f32 v[2:3], v[140:141], v[140:141]
	v_pk_mul_f32 v[0:1], v[142:143], v[142:143]
	v_add_f32_e32 v2, v2, v4
	v_add_f32_e32 v2, v3, v2
	v_add_f32_e32 v0, v0, v2
	v_and_b32_e32 v2, 64, v195
	v_add_f32_e32 v0, v1, v0
	v_xor_b32_e32 v1, 16, v195
	v_add_u32_e32 v2, 64, v2
	v_cmp_lt_i32_e32 vcc, v1, v2
	s_nop 1
	v_cndmask_b32_e32 v1, v195, v1, vcc
	v_lshlrev_b32_e32 v1, 2, v1
	ds_bpermute_b32 v1, v1, v0
	s_waitcnt lgkmcnt(0)
	v_add_f32_e32 v0, v0, v1
	v_xor_b32_e32 v1, 32, v195
	v_cmp_lt_i32_e32 vcc, v1, v2
	s_nop 1
	v_cndmask_b32_e32 v1, v195, v1, vcc
	v_lshlrev_b32_e32 v1, 2, v1
	ds_bpermute_b32 v1, v1, v0
	s_waitcnt lgkmcnt(0)
	v_add_f32_e32 v0, v0, v1
	v_mul_f32_e32 v1, v16, v16
	v_mul_f32_e32 v0, v1, v0
	v_fmamk_f32 v0, v0, 0x3c800000, v194
	v_mul_f32_e32 v1, 0x4b800000, v0
	v_cmp_gt_f32_e32 vcc, s42, v0
	s_nop 1
	v_cndmask_b32_e32 v0, v0, v1, vcc
	v_rsq_f32_e32 v0, v0
	s_nop 0
	v_mul_f32_e32 v1, 0x45800000, v0
	v_cndmask_b32_e32 v0, v0, v1, vcc
	v_mul_f32_e32 v0, v16, v0
	v_pk_mul_f32 v[18:19], v[128:129], v[0:1] op_sel_hi:[1,0]
	v_pk_mul_f32 v[2:3], v[130:131], v[0:1] op_sel_hi:[1,0]
	v_pk_mul_f32 v[4:5], v[132:133], v[0:1] op_sel_hi:[1,0]
	v_pk_mul_f32 v[6:7], v[134:135], v[0:1] op_sel_hi:[1,0]
	v_pk_mul_f32 v[8:9], v[136:137], v[0:1] op_sel_hi:[1,0]
	v_pk_mul_f32 v[10:11], v[138:139], v[0:1] op_sel_hi:[1,0]
	v_pk_mul_f32 v[12:13], v[140:141], v[0:1] op_sel_hi:[1,0]
	v_pk_mul_f32 v[0:1], v[142:143], v[0:1] op_sel_hi:[1,0]
	v_pk_mul_f32 v[12:13], v[174:175], v[12:13]
	v_pk_mul_f32 v[14:15], v[176:177], v[0:1]
	v_pk_mul_f32 v[10:11], v[172:173], v[10:11]
	v_pk_mul_f32 v[8:9], v[170:171], v[8:9]
	v_pk_mul_f32 v[6:7], v[168:169], v[6:7]
	v_pk_mul_f32 v[4:5], v[166:167], v[4:5]
	v_pk_mul_f32 v[2:3], v[164:165], v[2:3]
	v_pk_mul_f32 v[0:1], v[162:163], v[18:19]
	s_cbranch_execnz .LBB0_530
.LBB0_529:
	v_pk_mul_f32 v[14:15], v[142:143], v[16:17] op_sel_hi:[1,0]
	v_pk_mul_f32 v[10:11], v[138:139], v[16:17] op_sel_hi:[1,0]
	v_pk_mul_f32 v[6:7], v[134:135], v[16:17] op_sel_hi:[1,0]
	v_pk_mul_f32 v[2:3], v[130:131], v[16:17] op_sel_hi:[1,0]
	v_pk_mul_f32 v[12:13], v[140:141], v[16:17] op_sel_hi:[1,0]
	v_pk_mul_f32 v[8:9], v[136:137], v[16:17] op_sel_hi:[1,0]
	v_pk_mul_f32 v[4:5], v[132:133], v[16:17] op_sel_hi:[1,0]
	v_pk_mul_f32 v[0:1], v[128:129], v[16:17] op_sel_hi:[1,0]
.LBB0_530:
	s_and_saveexec_b64 s[4:5], s[70:71]
	s_cbranch_execz .LBB0_532
	s_waitcnt vmcnt(2)
	v_pk_mul_f32 v[16:17], v[8:9], v[204:205]
	v_pk_fma_f32 v[16:17], v[0:1], v[200:201], v[16:17] neg_lo:[0,0,1] neg_hi:[0,0,1]
	v_pk_mul_f32 v[0:1], v[0:1], v[204:205]
	s_nop 0
	v_pk_fma_f32 v[200:201], v[8:9], v[200:201], v[0:1]
	v_pk_mul_f32 v[0:1], v[10:11], v[206:207]
	s_nop 0
	v_pk_fma_f32 v[204:205], v[2:3], v[202:203], v[0:1] neg_lo:[0,0,1] neg_hi:[0,0,1]
	v_pk_mul_f32 v[0:1], v[2:3], v[206:207]
	v_mul_f32_e32 v2, v6, v210
	v_pk_fma_f32 v[202:203], v[10:11], v[202:203], v[0:1]
	v_pk_mul_f32 v[0:1], v[12:13], v[208:209]
	s_nop 0
	v_pk_fma_f32 v[206:207], v[4:5], v[212:213], v[0:1] neg_lo:[0,0,1] neg_hi:[0,0,1]
	v_pk_mul_f32 v[0:1], v[4:5], v[208:209]
	v_pk_mul_f32 v[4:5], v[14:15], v[210:211]
	v_mov_b32_e32 v210, v215
	v_pk_fma_f32 v[22:23], v[6:7], v[214:215], v[4:5] neg_lo:[0,0,1] neg_hi:[0,0,1]
	v_mov_b32_e32 v6, v15
	v_pk_mul_f32 v[4:5], v[6:7], v[210:211]
	v_pk_fma_f32 v[208:209], v[12:13], v[212:213], v[0:1]
	v_mul_f32_e32 v0, v14, v214
	v_mov_b32_e32 v1, v4
	v_mov_b32_e32 v3, v5
	v_pk_add_f32 v[210:211], v[0:1], v[2:3]
	s_nop 0
	v_mov_b64_e32 v[0:1], v[16:17]
	v_mov_b64_e32 v[2:3], v[204:205]
	v_mov_b64_e32 v[4:5], v[206:207]
	v_mov_b64_e32 v[6:7], v[22:23]
	v_mov_b64_e32 v[8:9], v[200:201]
	v_mov_b64_e32 v[10:11], v[202:203]
	v_mov_b64_e32 v[12:13], v[208:209]
	v_mov_b64_e32 v[14:15], v[210:211]
	global_load_dwordx4 v[208:211], v[216:217], off offset:2096
	global_load_dwordx4 v[212:215], v[216:217], off offset:2064
	global_load_dwordx4 v[204:207], v[216:217], off offset:2080
	global_load_dwordx4 v[200:203], v[216:217], off offset:2048
.LBB0_532:
	s_or_b64 exec, exec, s[4:5]
	v_lshlrev_b32_e32 v16, 7, v186
	v_and_b32_e32 v150, 0x3ef80, v16
	v_lshl_add_u64 v[16:17], v[182:183], 0, v[150:151]
	v_cvt_pk_bf16_f32 v0, v0, v1
	v_cvt_pk_bf16_f32 v1, v2, v3
	v_cvt_pk_bf16_f32 v2, v4, v5
	v_cvt_pk_bf16_f32 v3, v6, v7
	v_cvt_pk_bf16_f32 v4, v8, v9
	v_cvt_pk_bf16_f32 v5, v10, v11
	v_cvt_pk_bf16_f32 v6, v12, v13
	v_cvt_pk_bf16_f32 v7, v14, v15
	global_store_dwordx4 v[16:17], v[0:3], off
	global_store_dwordx4 v[16:17], v[4:7], off offset:16
.LBB0_533:
	v_or_b32_e32 v128, 32, v184
	v_ashrrev_i32_e32 v129, 31, v128
	v_lshl_add_u64 v[0:1], v[128:129], 2, s[26:27]
	v_mov_b32_e32 v16, v242
	s_and_b64 vcc, exec, s[14:15]
	s_mov_b64 s[4:5], -1
	s_cbranch_vccnz .LBB0_542
	s_and_b64 vcc, exec, s[12:13]
	s_cbranch_vccnz .LBB0_539
	s_and_saveexec_b64 s[4:5], s[6:7]
	s_cbranch_execz .LBB0_538
	v_mul_f32_e32 v0, v112, v16
	v_mul_f32_e32 v0, 0xbfb8aa3b, v0
	v_mul_f32_e32 v1, v113, v16
	v_exp_f32_e32 v0, v0
	v_mul_f32_e32 v1, 0xbfb8aa3b, v1
	v_exp_f32_e32 v1, v1
	v_mul_f32_e32 v3, v115, v16
	v_add_f32_e32 v0, 1.0, v0
	v_rcp_f32_e32 v2, v0
	v_add_f32_e32 v0, 1.0, v1
	v_mul_f32_e32 v1, v114, v16
	v_mul_f32_e32 v1, 0xbfb8aa3b, v1
	v_exp_f32_e32 v1, v1
	v_mul_f32_e32 v3, 0xbfb8aa3b, v3
	v_exp_f32_e32 v5, v3
	v_rcp_f32_e32 v3, v0
	v_add_f32_e32 v0, 1.0, v1
	v_mul_f32_e32 v1, v116, v16
	v_rcp_f32_e32 v4, v0
	v_add_f32_e32 v0, 1.0, v5
	v_mul_f32_e32 v1, 0xbfb8aa3b, v1
	v_mul_f32_e32 v5, v117, v16
	v_exp_f32_e32 v1, v1
	v_mul_f32_e32 v5, 0xbfb8aa3b, v5
	v_exp_f32_e32 v7, v5
	v_rcp_f32_e32 v5, v0
	v_add_f32_e32 v0, 1.0, v1
	v_mul_f32_e32 v1, v118, v16
	v_rcp_f32_e32 v6, v0
	v_add_f32_e32 v0, 1.0, v7
	v_mul_f32_e32 v1, 0xbfb8aa3b, v1
	v_mul_f32_e32 v7, v119, v16
	v_exp_f32_e32 v1, v1
	v_mul_f32_e32 v7, 0xbfb8aa3b, v7
	v_exp_f32_e32 v9, v7
	v_rcp_f32_e32 v7, v0
	v_add_f32_e32 v0, 1.0, v1
	v_rcp_f32_e32 v8, v0
	v_add_f32_e32 v0, 1.0, v9
	v_rcp_f32_e32 v9, v0
	v_lshlrev_b64 v[0:1], 7, v[128:129]
	v_lshl_add_u64 v[0:1], v[154:155], 0, v[0:1]
	global_store_dwordx4 v[0:1], v[2:5], off
	global_store_dwordx4 v[0:1], v[6:9], off offset:16
	s_and_b64 exec, exec, s[8:9]
	s_cbranch_execz .LBB0_538
	v_mul_f32_e32 v2, v120, v16
	v_mul_f32_e32 v3, v121, v16
	v_mul_f32_e32 v4, v122, v16
	v_mul_f32_e32 v5, v123, v16
	v_mul_f32_e32 v2, 0xbfb8aa3b, v2
	v_mul_f32_e32 v3, 0xbfb8aa3b, v3
	v_mul_f32_e32 v4, 0xbfb8aa3b, v4
	v_mul_f32_e32 v5, 0xbfb8aa3b, v5
	v_mul_f32_e32 v6, v124, v16
	v_mul_f32_e32 v7, v125, v16
	v_mul_f32_e32 v8, v126, v16
	v_mul_f32_e32 v9, v127, v16
	v_exp_f32_e32 v2, v2
	v_exp_f32_e32 v3, v3
	v_exp_f32_e32 v4, v4
	v_exp_f32_e32 v5, v5
	v_mul_f32_e32 v6, 0xbfb8aa3b, v6
	v_mul_f32_e32 v7, 0xbfb8aa3b, v7
	v_mul_f32_e32 v8, 0xbfb8aa3b, v8
	v_mul_f32_e32 v9, 0xbfb8aa3b, v9
	v_exp_f32_e32 v6, v6
	v_exp_f32_e32 v7, v7
	v_exp_f32_e32 v8, v8
	v_exp_f32_e32 v9, v9
	v_add_f32_e32 v2, 1.0, v2
	v_add_f32_e32 v3, 1.0, v3
	v_add_f32_e32 v4, 1.0, v4
	v_add_f32_e32 v5, 1.0, v5
	v_rcp_f32_e32 v2, v2
	v_rcp_f32_e32 v3, v3
	v_rcp_f32_e32 v4, v4
	v_rcp_f32_e32 v5, v5
	v_add_f32_e32 v6, 1.0, v6
	v_add_f32_e32 v7, 1.0, v7
	v_add_f32_e32 v8, 1.0, v8
	v_add_f32_e32 v9, 1.0, v9
	v_rcp_f32_e32 v6, v6
	v_rcp_f32_e32 v7, v7
	v_rcp_f32_e32 v8, v8
	v_rcp_f32_e32 v9, v9
	global_store_dwordx4 v[0:1], v[2:5], off offset:32
	global_store_dwordx4 v[0:1], v[6:9], off offset:48

.LBB0_539:
	s_andn2_b64 vcc, exec, s[4:5]
	s_cbranch_vccnz .LBB0_541
	v_mul_f32_e32 v3, 0xbfb8aa3b, v16
	v_mul_f32_e32 v0, v112, v3
	v_exp_f32_e32 v0, v0
	v_mul_f32_e32 v1, v113, v3
	v_exp_f32_e32 v1, v1
	v_mul_f32_e32 v2, v114, v3
	v_fmamk_f32 v0, v0, 0x3b808081, v193
	v_rcp_f32_e32 v0, v0
	v_fmamk_f32 v1, v1, 0x3b808081, v193
	v_rcp_f32_e32 v1, v1
	v_exp_f32_e32 v2, v2
	v_cvt_pk_u8_f32 v0, v0, 0, 0
	v_mul_f32_e32 v4, v116, v3
	v_cvt_pk_u8_f32 v0, v1, 1, v0
	v_fmamk_f32 v1, v2, 0x3b808081, v193
	v_mul_f32_e32 v2, v115, v3
	v_exp_f32_e32 v4, v4
	v_exp_f32_e32 v2, v2
	v_rcp_f32_e32 v1, v1
	v_mul_f32_e32 v5, v117, v3
	v_fmamk_f32 v4, v4, 0x3b808081, v193
	v_fmamk_f32 v2, v2, 0x3b808081, v193
	v_rcp_f32_e32 v4, v4
	v_rcp_f32_e32 v2, v2
	v_exp_f32_e32 v5, v5
	v_cvt_pk_u8_f32 v0, v1, 2, v0
	v_cvt_pk_u8_f32 v1, v4, 0, 0
	v_mul_f32_e32 v4, v118, v3
	v_cvt_pk_u8_f32 v0, v2, 3, v0
	v_fmamk_f32 v2, v5, 0x3b808081, v193
	v_exp_f32_e32 v4, v4
	v_mul_f32_e32 v5, v119, v3
	v_exp_f32_e32 v5, v5
	v_rcp_f32_e32 v2, v2
	v_fmamk_f32 v4, v4, 0x3b808081, v193
	v_rcp_f32_e32 v4, v4
	v_fmamk_f32 v5, v5, 0x3b808081, v193
	v_rcp_f32_e32 v5, v5
	v_mul_f32_e32 v6, v120, v3
	v_cvt_pk_u8_f32 v1, v2, 1, v1
	v_exp_f32_e32 v6, v6
	v_cvt_pk_u8_f32 v1, v4, 2, v1
	v_mul_f32_e32 v4, v121, v3
	v_cvt_pk_u8_f32 v1, v5, 3, v1
	v_exp_f32_e32 v4, v4
	v_mul_f32_e32 v5, v122, v3
	v_exp_f32_e32 v5, v5
	v_fmamk_f32 v2, v6, 0x3b808081, v193
	v_rcp_f32_e32 v2, v2
	v_fmamk_f32 v4, v4, 0x3b808081, v193
	v_rcp_f32_e32 v4, v4
	v_fmamk_f32 v5, v5, 0x3b808081, v193
	v_mul_f32_e32 v6, v123, v3
	v_rcp_f32_e32 v5, v5
	v_exp_f32_e32 v6, v6
	v_cvt_pk_u8_f32 v2, v2, 0, 0
	v_cvt_pk_u8_f32 v2, v4, 1, v2
	v_cvt_pk_u8_f32 v2, v5, 2, v2
	v_fmamk_f32 v4, v6, 0x3b808081, v193
	v_mul_f32_e32 v5, v124, v3
	v_mul_f32_e32 v6, v125, v3
	v_rcp_f32_e32 v4, v4
	v_exp_f32_e32 v5, v5
	v_exp_f32_e32 v6, v6
	v_cvt_pk_u8_f32 v2, v4, 3, v2
	v_fmamk_f32 v4, v5, 0x3b808081, v193
	v_fmamk_f32 v5, v6, 0x3b808081, v193
	v_mul_f32_e32 v6, v126, v3
	v_exp_f32_e32 v6, v6
	v_mul_f32_e32 v3, v127, v3
	v_exp_f32_e32 v3, v3
	v_rcp_f32_e32 v4, v4
	v_rcp_f32_e32 v5, v5
	v_fmamk_f32 v6, v6, 0x3b808081, v193
	v_rcp_f32_e32 v6, v6
	v_fmamk_f32 v3, v3, 0x3b808081, v193
	v_rcp_f32_e32 v3, v3
	v_cvt_pk_u8_f32 v4, v4, 0, 0
	v_cvt_pk_u8_f32 v4, v5, 1, v4
	v_cvt_pk_u8_f32 v4, v6, 2, v4
	v_cvt_pk_u8_f32 v3, v3, 3, v4
	v_lshlrev_b64 v[4:5], 10, v[128:129]
	v_lshl_add_u64 v[4:5], v[178:179], 0, v[4:5]
	global_store_dwordx4 v[4:5], v[0:3], off

.LBB0_542:
	s_andn2_b64 vcc, exec, s[4:5]
	s_cbranch_vccnz .LBB0_549
	s_and_b64 vcc, exec, s[10:11]
	s_cbranch_vccnz .LBB0_634
	v_mul_f32_e32 v4, v113, v113
	v_fmac_f32_e32 v4, v112, v112
	v_fmac_f32_e32 v4, v114, v114
	v_fmac_f32_e32 v4, v115, v115
	v_fmac_f32_e32 v4, v116, v116
	v_fmac_f32_e32 v4, v117, v117
	v_fmac_f32_e32 v4, v118, v118
	v_fmac_f32_e32 v4, v119, v119
	v_pk_mul_f32 v[2:3], v[120:121], v[120:121]
	v_pk_mul_f32 v[0:1], v[122:123], v[122:123]
	v_add_f32_e32 v2, v2, v4
	v_add_f32_e32 v2, v3, v2
	v_add_f32_e32 v0, v0, v2
	v_add_f32_e32 v4, v1, v0
	v_pk_mul_f32 v[2:3], v[124:125], v[124:125]
	v_pk_mul_f32 v[0:1], v[126:127], v[126:127]
	v_add_f32_e32 v2, v2, v4
	v_add_f32_e32 v2, v3, v2
	v_add_f32_e32 v0, v0, v2
	v_and_b32_e32 v2, 64, v195
	v_add_f32_e32 v0, v1, v0
	v_xor_b32_e32 v1, 16, v195
	v_add_u32_e32 v2, 64, v2
	v_cmp_lt_i32_e32 vcc, v1, v2
	s_nop 1
	v_cndmask_b32_e32 v1, v195, v1, vcc
	v_lshlrev_b32_e32 v1, 2, v1
	ds_bpermute_b32 v1, v1, v0
	s_waitcnt lgkmcnt(0)
	v_add_f32_e32 v0, v0, v1
	v_xor_b32_e32 v1, 32, v195
	v_cmp_lt_i32_e32 vcc, v1, v2
	s_nop 1
	v_cndmask_b32_e32 v1, v195, v1, vcc
	v_lshlrev_b32_e32 v1, 2, v1
	ds_bpermute_b32 v1, v1, v0
	s_waitcnt lgkmcnt(0)
	v_add_f32_e32 v0, v0, v1
	v_mul_f32_e32 v1, v16, v16
	v_mul_f32_e32 v0, v1, v0
	v_fmamk_f32 v0, v0, 0x3c800000, v194
	v_mul_f32_e32 v1, 0x4b800000, v0
	v_cmp_gt_f32_e32 vcc, s42, v0
	s_nop 1
	v_cndmask_b32_e32 v0, v0, v1, vcc
	v_rsq_f32_e32 v0, v0
	s_nop 0
	v_mul_f32_e32 v1, 0x45800000, v0
	v_cndmask_b32_e32 v0, v0, v1, vcc
	v_mul_f32_e32 v0, v16, v0
	v_pk_mul_f32 v[18:19], v[112:113], v[0:1] op_sel_hi:[1,0]
	v_pk_mul_f32 v[2:3], v[114:115], v[0:1] op_sel_hi:[1,0]
	v_pk_mul_f32 v[4:5], v[116:117], v[0:1] op_sel_hi:[1,0]
	v_pk_mul_f32 v[6:7], v[118:119], v[0:1] op_sel_hi:[1,0]
	v_pk_mul_f32 v[8:9], v[120:121], v[0:1] op_sel_hi:[1,0]
	v_pk_mul_f32 v[10:11], v[122:123], v[0:1] op_sel_hi:[1,0]
	v_pk_mul_f32 v[12:13], v[124:125], v[0:1] op_sel_hi:[1,0]
	v_pk_mul_f32 v[0:1], v[126:127], v[0:1] op_sel_hi:[1,0]
	v_pk_mul_f32 v[12:13], v[174:175], v[12:13]
	v_pk_mul_f32 v[14:15], v[176:177], v[0:1]
	v_pk_mul_f32 v[10:11], v[172:173], v[10:11]
	v_pk_mul_f32 v[8:9], v[170:171], v[8:9]
	v_pk_mul_f32 v[6:7], v[168:169], v[6:7]
	v_pk_mul_f32 v[4:5], v[166:167], v[4:5]
	v_pk_mul_f32 v[2:3], v[164:165], v[2:3]
	v_pk_mul_f32 v[0:1], v[162:163], v[18:19]
	s_cbranch_execnz .LBB0_546
.LBB0_545:
	v_pk_mul_f32 v[14:15], v[126:127], v[16:17] op_sel_hi:[1,0]
	v_pk_mul_f32 v[10:11], v[122:123], v[16:17] op_sel_hi:[1,0]
	v_pk_mul_f32 v[6:7], v[118:119], v[16:17] op_sel_hi:[1,0]
	v_pk_mul_f32 v[2:3], v[114:115], v[16:17] op_sel_hi:[1,0]
	v_pk_mul_f32 v[12:13], v[124:125], v[16:17] op_sel_hi:[1,0]
	v_pk_mul_f32 v[8:9], v[120:121], v[16:17] op_sel_hi:[1,0]
	v_pk_mul_f32 v[4:5], v[116:117], v[16:17] op_sel_hi:[1,0]
	v_pk_mul_f32 v[0:1], v[112:113], v[16:17] op_sel_hi:[1,0]
.LBB0_546:
	s_and_saveexec_b64 s[4:5], s[70:71]
	s_cbranch_execz .LBB0_548
	s_waitcnt vmcnt(2)
	v_pk_mul_f32 v[16:17], v[8:9], v[204:205]
	v_pk_fma_f32 v[16:17], v[0:1], v[200:201], v[16:17] neg_lo:[0,0,1] neg_hi:[0,0,1]
	v_pk_mul_f32 v[0:1], v[0:1], v[204:205]
	s_nop 0
	v_pk_fma_f32 v[200:201], v[8:9], v[200:201], v[0:1]
	v_pk_mul_f32 v[0:1], v[10:11], v[206:207]
	s_nop 0
	v_pk_fma_f32 v[204:205], v[2:3], v[202:203], v[0:1] neg_lo:[0,0,1] neg_hi:[0,0,1]
	v_pk_mul_f32 v[0:1], v[2:3], v[206:207]
	v_mul_f32_e32 v2, v6, v210
	v_pk_fma_f32 v[202:203], v[10:11], v[202:203], v[0:1]
	v_pk_mul_f32 v[0:1], v[12:13], v[208:209]
	s_nop 0
	v_pk_fma_f32 v[206:207], v[4:5], v[212:213], v[0:1] neg_lo:[0,0,1] neg_hi:[0,0,1]
	v_pk_mul_f32 v[0:1], v[4:5], v[208:209]
	v_pk_mul_f32 v[4:5], v[14:15], v[210:211]
	v_mov_b32_e32 v210, v215
	v_pk_fma_f32 v[22:23], v[6:7], v[214:215], v[4:5] neg_lo:[0,0,1] neg_hi:[0,0,1]
	v_mov_b32_e32 v6, v15
	v_pk_mul_f32 v[4:5], v[6:7], v[210:211]
	v_pk_fma_f32 v[208:209], v[12:13], v[212:213], v[0:1]
	v_mul_f32_e32 v0, v14, v214
	v_mov_b32_e32 v1, v4
	v_mov_b32_e32 v3, v5
	v_pk_add_f32 v[210:211], v[0:1], v[2:3]
	s_nop 0
	v_mov_b64_e32 v[0:1], v[16:17]
	v_mov_b64_e32 v[2:3], v[204:205]
	v_mov_b64_e32 v[4:5], v[206:207]
	v_mov_b64_e32 v[6:7], v[22:23]
	v_mov_b64_e32 v[8:9], v[200:201]
	v_mov_b64_e32 v[10:11], v[202:203]
	v_mov_b64_e32 v[12:13], v[208:209]
	v_mov_b64_e32 v[14:15], v[210:211]
	global_load_dwordx4 v[208:211], v[216:217], off offset:3120
	global_load_dwordx4 v[212:215], v[216:217], off offset:3088
	global_load_dwordx4 v[204:207], v[216:217], off offset:3104
	global_load_dwordx4 v[200:203], v[216:217], off offset:3072
.LBB0_548:
	s_or_b64 exec, exec, s[4:5]
	v_lshlrev_b32_e32 v16, 7, v128
	v_and_b32_e32 v150, 0x3f780, v16
	v_lshl_add_u64 v[16:17], v[182:183], 0, v[150:151]
	v_cvt_pk_bf16_f32 v0, v0, v1
	v_cvt_pk_bf16_f32 v1, v2, v3
	v_cvt_pk_bf16_f32 v2, v4, v5
	v_cvt_pk_bf16_f32 v3, v6, v7
	v_cvt_pk_bf16_f32 v4, v8, v9
	v_cvt_pk_bf16_f32 v5, v10, v11
	v_cvt_pk_bf16_f32 v6, v12, v13
	v_cvt_pk_bf16_f32 v7, v14, v15
	global_store_dwordx4 v[16:17], v[0:3], off
	global_store_dwordx4 v[16:17], v[4:7], off offset:16
.LBB0_549:
	v_or_b32_e32 v112, 48, v184
	v_ashrrev_i32_e32 v113, 31, v112
	v_lshl_add_u64 v[0:1], v[112:113], 2, s[26:27]
	v_mov_b32_e32 v16, v243
	s_and_b64 vcc, exec, s[14:15]
	s_mov_b64 s[4:5], -1
	s_cbranch_vccnz .LBB0_558
	s_and_b64 vcc, exec, s[12:13]
	s_cbranch_vccnz .LBB0_555
	s_and_saveexec_b64 s[4:5], s[6:7]
	s_cbranch_execz .LBB0_554
	v_mul_f32_e32 v0, v96, v16
	v_mul_f32_e32 v0, 0xbfb8aa3b, v0
	v_mul_f32_e32 v1, v97, v16
	v_exp_f32_e32 v0, v0
	v_mul_f32_e32 v1, 0xbfb8aa3b, v1
	v_exp_f32_e32 v1, v1
	v_mul_f32_e32 v3, v99, v16
	v_add_f32_e32 v0, 1.0, v0
	v_rcp_f32_e32 v2, v0
	v_add_f32_e32 v0, 1.0, v1
	v_mul_f32_e32 v1, v98, v16
	v_mul_f32_e32 v1, 0xbfb8aa3b, v1
	v_exp_f32_e32 v1, v1
	v_mul_f32_e32 v3, 0xbfb8aa3b, v3
	v_exp_f32_e32 v5, v3
	v_rcp_f32_e32 v3, v0
	v_add_f32_e32 v0, 1.0, v1
	v_mul_f32_e32 v1, v100, v16
	v_rcp_f32_e32 v4, v0
	v_add_f32_e32 v0, 1.0, v5
	v_mul_f32_e32 v1, 0xbfb8aa3b, v1
	v_mul_f32_e32 v5, v101, v16
	v_exp_f32_e32 v1, v1
	v_mul_f32_e32 v5, 0xbfb8aa3b, v5
	v_exp_f32_e32 v7, v5
	v_rcp_f32_e32 v5, v0
	v_add_f32_e32 v0, 1.0, v1
	v_mul_f32_e32 v1, v102, v16
	v_rcp_f32_e32 v6, v0
	v_add_f32_e32 v0, 1.0, v7
	v_mul_f32_e32 v1, 0xbfb8aa3b, v1
	v_mul_f32_e32 v7, v103, v16
	v_exp_f32_e32 v1, v1
	v_mul_f32_e32 v7, 0xbfb8aa3b, v7
	v_exp_f32_e32 v9, v7
	v_rcp_f32_e32 v7, v0
	v_add_f32_e32 v0, 1.0, v1
	v_rcp_f32_e32 v8, v0
	v_add_f32_e32 v0, 1.0, v9
	v_rcp_f32_e32 v9, v0
	v_lshlrev_b64 v[0:1], 7, v[112:113]
	v_lshl_add_u64 v[0:1], v[154:155], 0, v[0:1]
	global_store_dwordx4 v[0:1], v[2:5], off
	global_store_dwordx4 v[0:1], v[6:9], off offset:16
	s_and_b64 exec, exec, s[8:9]
	s_cbranch_execz .LBB0_554
	v_mul_f32_e32 v2, v104, v16
	v_mul_f32_e32 v3, v105, v16
	v_mul_f32_e32 v4, v106, v16
	v_mul_f32_e32 v5, v107, v16
	v_mul_f32_e32 v2, 0xbfb8aa3b, v2
	v_mul_f32_e32 v3, 0xbfb8aa3b, v3
	v_mul_f32_e32 v4, 0xbfb8aa3b, v4
	v_mul_f32_e32 v5, 0xbfb8aa3b, v5
	v_mul_f32_e32 v6, v108, v16
	v_mul_f32_e32 v7, v109, v16
	v_mul_f32_e32 v8, v110, v16
	v_mul_f32_e32 v9, v111, v16
	v_exp_f32_e32 v2, v2
	v_exp_f32_e32 v3, v3
	v_exp_f32_e32 v4, v4
	v_exp_f32_e32 v5, v5
	v_mul_f32_e32 v6, 0xbfb8aa3b, v6
	v_mul_f32_e32 v7, 0xbfb8aa3b, v7
	v_mul_f32_e32 v8, 0xbfb8aa3b, v8
	v_mul_f32_e32 v9, 0xbfb8aa3b, v9
	v_exp_f32_e32 v6, v6
	v_exp_f32_e32 v7, v7
	v_exp_f32_e32 v8, v8
	v_exp_f32_e32 v9, v9
	v_add_f32_e32 v2, 1.0, v2
	v_add_f32_e32 v3, 1.0, v3
	v_add_f32_e32 v4, 1.0, v4
	v_add_f32_e32 v5, 1.0, v5
	v_rcp_f32_e32 v2, v2
	v_rcp_f32_e32 v3, v3
	v_rcp_f32_e32 v4, v4
	v_rcp_f32_e32 v5, v5
	v_add_f32_e32 v6, 1.0, v6
	v_add_f32_e32 v7, 1.0, v7
	v_add_f32_e32 v8, 1.0, v8
	v_add_f32_e32 v9, 1.0, v9
	v_rcp_f32_e32 v6, v6
	v_rcp_f32_e32 v7, v7
	v_rcp_f32_e32 v8, v8
	v_rcp_f32_e32 v9, v9
	global_store_dwordx4 v[0:1], v[2:5], off offset:32
	global_store_dwordx4 v[0:1], v[6:9], off offset:48

.LBB0_555:
	s_andn2_b64 vcc, exec, s[4:5]
	s_cbranch_vccnz .LBB0_557
	v_mul_f32_e32 v3, 0xbfb8aa3b, v16
	v_mul_f32_e32 v0, v96, v3
	v_exp_f32_e32 v0, v0
	v_mul_f32_e32 v1, v97, v3
	v_exp_f32_e32 v1, v1
	v_mul_f32_e32 v2, v98, v3
	v_fmamk_f32 v0, v0, 0x3b808081, v193
	v_rcp_f32_e32 v0, v0
	v_fmamk_f32 v1, v1, 0x3b808081, v193
	v_rcp_f32_e32 v1, v1
	v_exp_f32_e32 v2, v2
	v_cvt_pk_u8_f32 v0, v0, 0, 0
	v_mul_f32_e32 v4, v100, v3
	v_cvt_pk_u8_f32 v0, v1, 1, v0
	v_fmamk_f32 v1, v2, 0x3b808081, v193
	v_mul_f32_e32 v2, v99, v3
	v_exp_f32_e32 v4, v4
	v_exp_f32_e32 v2, v2
	v_rcp_f32_e32 v1, v1
	v_mul_f32_e32 v5, v101, v3
	v_fmamk_f32 v4, v4, 0x3b808081, v193
	v_fmamk_f32 v2, v2, 0x3b808081, v193
	v_rcp_f32_e32 v4, v4
	v_rcp_f32_e32 v2, v2
	v_exp_f32_e32 v5, v5
	v_cvt_pk_u8_f32 v0, v1, 2, v0
	v_cvt_pk_u8_f32 v1, v4, 0, 0
	v_mul_f32_e32 v4, v102, v3
	v_cvt_pk_u8_f32 v0, v2, 3, v0
	v_fmamk_f32 v2, v5, 0x3b808081, v193
	v_exp_f32_e32 v4, v4
	v_mul_f32_e32 v5, v103, v3
	v_exp_f32_e32 v5, v5
	v_rcp_f32_e32 v2, v2
	v_fmamk_f32 v4, v4, 0x3b808081, v193
	v_rcp_f32_e32 v4, v4
	v_fmamk_f32 v5, v5, 0x3b808081, v193
	v_rcp_f32_e32 v5, v5
	v_mul_f32_e32 v6, v104, v3
	v_cvt_pk_u8_f32 v1, v2, 1, v1
	v_exp_f32_e32 v6, v6
	v_cvt_pk_u8_f32 v1, v4, 2, v1
	v_mul_f32_e32 v4, v105, v3
	v_cvt_pk_u8_f32 v1, v5, 3, v1
	v_exp_f32_e32 v4, v4
	v_mul_f32_e32 v5, v106, v3
	v_exp_f32_e32 v5, v5
	v_fmamk_f32 v2, v6, 0x3b808081, v193
	v_rcp_f32_e32 v2, v2
	v_fmamk_f32 v4, v4, 0x3b808081, v193
	v_rcp_f32_e32 v4, v4
	v_fmamk_f32 v5, v5, 0x3b808081, v193
	v_mul_f32_e32 v6, v107, v3
	v_rcp_f32_e32 v5, v5
	v_exp_f32_e32 v6, v6
	v_cvt_pk_u8_f32 v2, v2, 0, 0
	v_cvt_pk_u8_f32 v2, v4, 1, v2
	v_cvt_pk_u8_f32 v2, v5, 2, v2
	v_fmamk_f32 v4, v6, 0x3b808081, v193
	v_mul_f32_e32 v5, v108, v3
	v_mul_f32_e32 v6, v109, v3
	v_rcp_f32_e32 v4, v4
	v_exp_f32_e32 v5, v5
	v_exp_f32_e32 v6, v6
	v_cvt_pk_u8_f32 v2, v4, 3, v2
	v_fmamk_f32 v4, v5, 0x3b808081, v193
	v_fmamk_f32 v5, v6, 0x3b808081, v193
	v_mul_f32_e32 v6, v110, v3
	v_exp_f32_e32 v6, v6
	v_mul_f32_e32 v3, v111, v3
	v_exp_f32_e32 v3, v3
	v_rcp_f32_e32 v4, v4
	v_rcp_f32_e32 v5, v5
	v_fmamk_f32 v6, v6, 0x3b808081, v193
	v_rcp_f32_e32 v6, v6
	v_fmamk_f32 v3, v3, 0x3b808081, v193
	v_rcp_f32_e32 v3, v3
	v_cvt_pk_u8_f32 v4, v4, 0, 0
	v_cvt_pk_u8_f32 v4, v5, 1, v4
	v_cvt_pk_u8_f32 v4, v6, 2, v4
	v_cvt_pk_u8_f32 v3, v3, 3, v4
	v_lshlrev_b64 v[4:5], 10, v[112:113]
	v_lshl_add_u64 v[4:5], v[178:179], 0, v[4:5]
	global_store_dwordx4 v[4:5], v[0:3], off

.LBB0_558:
	s_andn2_b64 vcc, exec, s[4:5]
	s_cbranch_vccnz .LBB0_565
	s_and_b64 vcc, exec, s[10:11]
	s_cbranch_vccnz .LBB0_635
	v_mul_f32_e32 v4, v97, v97
	v_fmac_f32_e32 v4, v96, v96
	v_fmac_f32_e32 v4, v98, v98
	v_fmac_f32_e32 v4, v99, v99
	v_fmac_f32_e32 v4, v100, v100
	v_fmac_f32_e32 v4, v101, v101
	v_fmac_f32_e32 v4, v102, v102
	v_fmac_f32_e32 v4, v103, v103
	v_pk_mul_f32 v[2:3], v[104:105], v[104:105]
	v_pk_mul_f32 v[0:1], v[106:107], v[106:107]
	v_add_f32_e32 v2, v2, v4
	v_add_f32_e32 v2, v3, v2
	v_add_f32_e32 v0, v0, v2
	v_add_f32_e32 v4, v1, v0
	v_pk_mul_f32 v[2:3], v[108:109], v[108:109]
	v_pk_mul_f32 v[0:1], v[110:111], v[110:111]
	v_add_f32_e32 v2, v2, v4
	v_add_f32_e32 v2, v3, v2
	v_add_f32_e32 v0, v0, v2
	v_and_b32_e32 v2, 64, v195
	v_add_f32_e32 v0, v1, v0
	v_xor_b32_e32 v1, 16, v195
	v_add_u32_e32 v2, 64, v2
	v_cmp_lt_i32_e32 vcc, v1, v2
	s_nop 1
	v_cndmask_b32_e32 v1, v195, v1, vcc
	v_lshlrev_b32_e32 v1, 2, v1
	ds_bpermute_b32 v1, v1, v0
	s_waitcnt lgkmcnt(0)
	v_add_f32_e32 v0, v0, v1
	v_xor_b32_e32 v1, 32, v195
	v_cmp_lt_i32_e32 vcc, v1, v2
	s_nop 1
	v_cndmask_b32_e32 v1, v195, v1, vcc
	v_lshlrev_b32_e32 v1, 2, v1
	ds_bpermute_b32 v1, v1, v0
	s_waitcnt lgkmcnt(0)
	v_add_f32_e32 v0, v0, v1
	v_mul_f32_e32 v1, v16, v16
	v_mul_f32_e32 v0, v1, v0
	v_fmamk_f32 v0, v0, 0x3c800000, v194
	v_mul_f32_e32 v1, 0x4b800000, v0
	v_cmp_gt_f32_e32 vcc, s42, v0
	s_nop 1
	v_cndmask_b32_e32 v0, v0, v1, vcc
	v_rsq_f32_e32 v0, v0
	s_nop 0
	v_mul_f32_e32 v1, 0x45800000, v0
	v_cndmask_b32_e32 v0, v0, v1, vcc
	v_mul_f32_e32 v0, v16, v0
	v_pk_mul_f32 v[18:19], v[96:97], v[0:1] op_sel_hi:[1,0]
	v_pk_mul_f32 v[2:3], v[98:99], v[0:1] op_sel_hi:[1,0]
	v_pk_mul_f32 v[4:5], v[100:101], v[0:1] op_sel_hi:[1,0]
	v_pk_mul_f32 v[6:7], v[102:103], v[0:1] op_sel_hi:[1,0]
	v_pk_mul_f32 v[8:9], v[104:105], v[0:1] op_sel_hi:[1,0]
	v_pk_mul_f32 v[10:11], v[106:107], v[0:1] op_sel_hi:[1,0]
	v_pk_mul_f32 v[12:13], v[108:109], v[0:1] op_sel_hi:[1,0]
	v_pk_mul_f32 v[0:1], v[110:111], v[0:1] op_sel_hi:[1,0]
	v_pk_mul_f32 v[12:13], v[174:175], v[12:13]
	v_pk_mul_f32 v[14:15], v[176:177], v[0:1]
	v_pk_mul_f32 v[10:11], v[172:173], v[10:11]
	v_pk_mul_f32 v[8:9], v[170:171], v[8:9]
	v_pk_mul_f32 v[6:7], v[168:169], v[6:7]
	v_pk_mul_f32 v[4:5], v[166:167], v[4:5]
	v_pk_mul_f32 v[2:3], v[164:165], v[2:3]
	v_pk_mul_f32 v[0:1], v[162:163], v[18:19]
	s_cbranch_execnz .LBB0_562
.LBB0_561:
	v_pk_mul_f32 v[14:15], v[110:111], v[16:17] op_sel_hi:[1,0]
	v_pk_mul_f32 v[10:11], v[106:107], v[16:17] op_sel_hi:[1,0]
	v_pk_mul_f32 v[6:7], v[102:103], v[16:17] op_sel_hi:[1,0]
	v_pk_mul_f32 v[2:3], v[98:99], v[16:17] op_sel_hi:[1,0]
	v_pk_mul_f32 v[12:13], v[108:109], v[16:17] op_sel_hi:[1,0]
	v_pk_mul_f32 v[8:9], v[104:105], v[16:17] op_sel_hi:[1,0]
	v_pk_mul_f32 v[4:5], v[100:101], v[16:17] op_sel_hi:[1,0]
	v_pk_mul_f32 v[0:1], v[96:97], v[16:17] op_sel_hi:[1,0]
.LBB0_562:
	s_and_saveexec_b64 s[4:5], s[70:71]
	s_cbranch_execz .LBB0_564
	s_waitcnt vmcnt(2)
	v_pk_mul_f32 v[16:17], v[8:9], v[204:205]
	v_pk_fma_f32 v[16:17], v[0:1], v[200:201], v[16:17] neg_lo:[0,0,1] neg_hi:[0,0,1]
	v_pk_mul_f32 v[0:1], v[0:1], v[204:205]
	s_nop 0
	v_pk_fma_f32 v[200:201], v[8:9], v[200:201], v[0:1]
	v_pk_mul_f32 v[0:1], v[10:11], v[206:207]
	s_nop 0
	v_pk_fma_f32 v[204:205], v[2:3], v[202:203], v[0:1] neg_lo:[0,0,1] neg_hi:[0,0,1]
	v_pk_mul_f32 v[0:1], v[2:3], v[206:207]
	v_mul_f32_e32 v2, v6, v210
	v_pk_fma_f32 v[202:203], v[10:11], v[202:203], v[0:1]
	v_pk_mul_f32 v[0:1], v[12:13], v[208:209]
	s_nop 0
	v_pk_fma_f32 v[206:207], v[4:5], v[212:213], v[0:1] neg_lo:[0,0,1] neg_hi:[0,0,1]
	v_pk_mul_f32 v[0:1], v[4:5], v[208:209]
	v_pk_mul_f32 v[4:5], v[14:15], v[210:211]
	v_mov_b32_e32 v210, v215
	v_pk_fma_f32 v[22:23], v[6:7], v[214:215], v[4:5] neg_lo:[0,0,1] neg_hi:[0,0,1]
	v_mov_b32_e32 v6, v15
	v_pk_mul_f32 v[4:5], v[6:7], v[210:211]
	v_pk_fma_f32 v[208:209], v[12:13], v[212:213], v[0:1]
	v_mul_f32_e32 v0, v14, v214
	v_mov_b32_e32 v1, v4
	v_mov_b32_e32 v3, v5
	v_pk_add_f32 v[210:211], v[0:1], v[2:3]
	s_nop 0
	v_mov_b64_e32 v[0:1], v[16:17]
	v_mov_b64_e32 v[2:3], v[204:205]
	v_mov_b64_e32 v[4:5], v[206:207]
	v_mov_b64_e32 v[6:7], v[22:23]
	v_mov_b64_e32 v[8:9], v[200:201]
	v_mov_b64_e32 v[10:11], v[202:203]
	v_mov_b64_e32 v[12:13], v[208:209]
	v_mov_b64_e32 v[14:15], v[210:211]
	global_load_dwordx4 v[208:211], v[218:219], off offset:48
	global_load_dwordx4 v[212:215], v[218:219], off offset:16
	global_load_dwordx4 v[204:207], v[218:219], off offset:32
	global_load_dwordx4 v[200:203], v[218:219], off offset:0
.LBB0_564:
	s_or_b64 exec, exec, s[4:5]
	v_lshlrev_b32_e32 v16, 7, v112
	v_and_b32_e32 v150, 0x3ff80, v16
	v_lshl_add_u64 v[16:17], v[182:183], 0, v[150:151]
	v_cvt_pk_bf16_f32 v0, v0, v1
	v_cvt_pk_bf16_f32 v1, v2, v3
	v_cvt_pk_bf16_f32 v2, v4, v5
	v_cvt_pk_bf16_f32 v3, v6, v7
	v_cvt_pk_bf16_f32 v4, v8, v9
	v_cvt_pk_bf16_f32 v5, v10, v11
	v_cvt_pk_bf16_f32 v6, v12, v13
	v_cvt_pk_bf16_f32 v7, v14, v15
	global_store_dwordx4 v[16:17], v[0:3], off
	global_store_dwordx4 v[16:17], v[4:7], off offset:16
.LBB0_565:
	s_addk_i32 s76, 0x80
	v_or_b32_e32 v98, s76, v149
	v_ashrrev_i32_e32 v99, 31, v98
	v_lshl_add_u64 v[0:1], v[98:99], 2, s[26:27]
	v_mov_b32_e32 v16, v244
	s_and_b64 vcc, exec, s[14:15]
	s_mov_b64 s[4:5], -1
	s_cbranch_vccnz .LBB0_574
	s_and_b64 vcc, exec, s[12:13]
	s_cbranch_vccnz .LBB0_571
	s_and_saveexec_b64 s[4:5], s[6:7]
	s_cbranch_execz .LBB0_570
	v_mul_f32_e32 v0, v80, v16
	v_mul_f32_e32 v0, 0xbfb8aa3b, v0
	v_mul_f32_e32 v1, v81, v16
	v_exp_f32_e32 v0, v0
	v_mul_f32_e32 v1, 0xbfb8aa3b, v1
	v_exp_f32_e32 v1, v1
	v_mul_f32_e32 v3, v83, v16
	v_add_f32_e32 v0, 1.0, v0
	v_rcp_f32_e32 v2, v0
	v_add_f32_e32 v0, 1.0, v1
	v_mul_f32_e32 v1, v82, v16
	v_mul_f32_e32 v1, 0xbfb8aa3b, v1
	v_exp_f32_e32 v1, v1
	v_mul_f32_e32 v3, 0xbfb8aa3b, v3
	v_exp_f32_e32 v5, v3
	v_rcp_f32_e32 v3, v0
	v_add_f32_e32 v0, 1.0, v1
	v_mul_f32_e32 v1, v84, v16
	v_rcp_f32_e32 v4, v0
	v_add_f32_e32 v0, 1.0, v5
	v_mul_f32_e32 v1, 0xbfb8aa3b, v1
	v_mul_f32_e32 v5, v85, v16
	v_exp_f32_e32 v1, v1
	v_mul_f32_e32 v5, 0xbfb8aa3b, v5
	v_exp_f32_e32 v7, v5
	v_rcp_f32_e32 v5, v0
	v_add_f32_e32 v0, 1.0, v1
	v_mul_f32_e32 v1, v86, v16
	v_rcp_f32_e32 v6, v0
	v_add_f32_e32 v0, 1.0, v7
	v_mul_f32_e32 v1, 0xbfb8aa3b, v1
	v_mul_f32_e32 v7, v87, v16
	v_exp_f32_e32 v1, v1
	v_mul_f32_e32 v7, 0xbfb8aa3b, v7
	v_exp_f32_e32 v9, v7
	v_rcp_f32_e32 v7, v0
	v_add_f32_e32 v0, 1.0, v1
	v_rcp_f32_e32 v8, v0
	v_add_f32_e32 v0, 1.0, v9
	v_rcp_f32_e32 v9, v0
	v_lshlrev_b64 v[0:1], 7, v[98:99]
	v_lshl_add_u64 v[0:1], v[154:155], 0, v[0:1]
	global_store_dwordx4 v[0:1], v[2:5], off
	global_store_dwordx4 v[0:1], v[6:9], off offset:16
	s_and_b64 exec, exec, s[8:9]
	s_cbranch_execz .LBB0_570
	v_mul_f32_e32 v2, v88, v16
	v_mul_f32_e32 v3, v89, v16
	v_mul_f32_e32 v4, v90, v16
	v_mul_f32_e32 v5, v91, v16
	v_mul_f32_e32 v2, 0xbfb8aa3b, v2
	v_mul_f32_e32 v3, 0xbfb8aa3b, v3
	v_mul_f32_e32 v4, 0xbfb8aa3b, v4
	v_mul_f32_e32 v5, 0xbfb8aa3b, v5
	v_mul_f32_e32 v6, v92, v16
	v_mul_f32_e32 v7, v93, v16
	v_mul_f32_e32 v8, v94, v16
	v_mul_f32_e32 v9, v95, v16
	v_exp_f32_e32 v2, v2
	v_exp_f32_e32 v3, v3
	v_exp_f32_e32 v4, v4
	v_exp_f32_e32 v5, v5
	v_mul_f32_e32 v6, 0xbfb8aa3b, v6
	v_mul_f32_e32 v7, 0xbfb8aa3b, v7
	v_mul_f32_e32 v8, 0xbfb8aa3b, v8
	v_mul_f32_e32 v9, 0xbfb8aa3b, v9
	v_exp_f32_e32 v6, v6
	v_exp_f32_e32 v7, v7
	v_exp_f32_e32 v8, v8
	v_exp_f32_e32 v9, v9
	v_add_f32_e32 v2, 1.0, v2
	v_add_f32_e32 v3, 1.0, v3
	v_add_f32_e32 v4, 1.0, v4
	v_add_f32_e32 v5, 1.0, v5
	v_rcp_f32_e32 v2, v2
	v_rcp_f32_e32 v3, v3
	v_rcp_f32_e32 v4, v4
	v_rcp_f32_e32 v5, v5
	v_add_f32_e32 v6, 1.0, v6
	v_add_f32_e32 v7, 1.0, v7
	v_add_f32_e32 v8, 1.0, v8
	v_add_f32_e32 v9, 1.0, v9
	v_rcp_f32_e32 v6, v6
	v_rcp_f32_e32 v7, v7
	v_rcp_f32_e32 v8, v8
	v_rcp_f32_e32 v9, v9
	global_store_dwordx4 v[0:1], v[2:5], off offset:32
	global_store_dwordx4 v[0:1], v[6:9], off offset:48

.LBB0_571:
	s_andn2_b64 vcc, exec, s[4:5]
	s_cbranch_vccnz .LBB0_573
	v_mul_f32_e32 v3, 0xbfb8aa3b, v16
	v_mul_f32_e32 v0, v80, v3
	v_exp_f32_e32 v0, v0
	v_mul_f32_e32 v1, v81, v3
	v_exp_f32_e32 v1, v1
	v_mul_f32_e32 v2, v82, v3
	v_fmamk_f32 v0, v0, 0x3b808081, v193
	v_rcp_f32_e32 v0, v0
	v_fmamk_f32 v1, v1, 0x3b808081, v193
	v_rcp_f32_e32 v1, v1
	v_exp_f32_e32 v2, v2
	v_cvt_pk_u8_f32 v0, v0, 0, 0
	v_mul_f32_e32 v4, v84, v3
	v_cvt_pk_u8_f32 v0, v1, 1, v0
	v_fmamk_f32 v1, v2, 0x3b808081, v193
	v_mul_f32_e32 v2, v83, v3
	v_exp_f32_e32 v4, v4
	v_exp_f32_e32 v2, v2
	v_rcp_f32_e32 v1, v1
	v_mul_f32_e32 v5, v85, v3
	v_fmamk_f32 v4, v4, 0x3b808081, v193
	v_fmamk_f32 v2, v2, 0x3b808081, v193
	v_rcp_f32_e32 v4, v4
	v_rcp_f32_e32 v2, v2
	v_exp_f32_e32 v5, v5
	v_cvt_pk_u8_f32 v0, v1, 2, v0
	v_cvt_pk_u8_f32 v1, v4, 0, 0
	v_mul_f32_e32 v4, v86, v3
	v_cvt_pk_u8_f32 v0, v2, 3, v0
	v_fmamk_f32 v2, v5, 0x3b808081, v193
	v_exp_f32_e32 v4, v4
	v_mul_f32_e32 v5, v87, v3
	v_exp_f32_e32 v5, v5
	v_rcp_f32_e32 v2, v2
	v_fmamk_f32 v4, v4, 0x3b808081, v193
	v_rcp_f32_e32 v4, v4
	v_fmamk_f32 v5, v5, 0x3b808081, v193
	v_rcp_f32_e32 v5, v5
	v_mul_f32_e32 v6, v88, v3
	v_cvt_pk_u8_f32 v1, v2, 1, v1
	v_exp_f32_e32 v6, v6
	v_cvt_pk_u8_f32 v1, v4, 2, v1
	v_mul_f32_e32 v4, v89, v3
	v_cvt_pk_u8_f32 v1, v5, 3, v1
	v_exp_f32_e32 v4, v4
	v_mul_f32_e32 v5, v90, v3
	v_exp_f32_e32 v5, v5
	v_fmamk_f32 v2, v6, 0x3b808081, v193
	v_rcp_f32_e32 v2, v2
	v_fmamk_f32 v4, v4, 0x3b808081, v193
	v_rcp_f32_e32 v4, v4
	v_fmamk_f32 v5, v5, 0x3b808081, v193
	v_mul_f32_e32 v6, v91, v3
	v_rcp_f32_e32 v5, v5
	v_exp_f32_e32 v6, v6
	v_cvt_pk_u8_f32 v2, v2, 0, 0
	v_cvt_pk_u8_f32 v2, v4, 1, v2
	v_cvt_pk_u8_f32 v2, v5, 2, v2
	v_fmamk_f32 v4, v6, 0x3b808081, v193
	v_mul_f32_e32 v5, v92, v3
	v_mul_f32_e32 v6, v93, v3
	v_rcp_f32_e32 v4, v4
	v_exp_f32_e32 v5, v5
	v_exp_f32_e32 v6, v6
	v_cvt_pk_u8_f32 v2, v4, 3, v2
	v_fmamk_f32 v4, v5, 0x3b808081, v193
	v_fmamk_f32 v5, v6, 0x3b808081, v193
	v_mul_f32_e32 v6, v94, v3
	v_exp_f32_e32 v6, v6
	v_mul_f32_e32 v3, v95, v3
	v_exp_f32_e32 v3, v3
	v_rcp_f32_e32 v4, v4
	v_rcp_f32_e32 v5, v5
	v_fmamk_f32 v6, v6, 0x3b808081, v193
	v_rcp_f32_e32 v6, v6
	v_fmamk_f32 v3, v3, 0x3b808081, v193
	v_rcp_f32_e32 v3, v3
	v_cvt_pk_u8_f32 v4, v4, 0, 0
	v_cvt_pk_u8_f32 v4, v5, 1, v4
	v_cvt_pk_u8_f32 v4, v6, 2, v4
	v_cvt_pk_u8_f32 v3, v3, 3, v4
	v_lshlrev_b64 v[4:5], 10, v[98:99]
	v_lshl_add_u64 v[4:5], v[178:179], 0, v[4:5]
	global_store_dwordx4 v[4:5], v[0:3], off

.LBB0_574:
	s_ashr_i32 s72, s76, 11
	s_mul_i32 s65, s65, s72
	s_add_i32 s72, s65, s63
	s_ashr_i32 s73, s72, 31
	s_lshl_b64 s[72:73], s[72:73], 18
	s_andn2_b64 vcc, exec, s[4:5]
	v_lshl_add_u64 v[96:97], v[180:181], 0, s[72:73]
	s_cbranch_vccnz .LBB0_581
	s_and_b64 vcc, exec, s[10:11]
	s_cbranch_vccnz .LBB0_636
	v_mul_f32_e32 v4, v81, v81
	v_fmac_f32_e32 v4, v80, v80
	v_fmac_f32_e32 v4, v82, v82
	v_fmac_f32_e32 v4, v83, v83
	v_fmac_f32_e32 v4, v84, v84
	v_fmac_f32_e32 v4, v85, v85
	v_fmac_f32_e32 v4, v86, v86
	v_fmac_f32_e32 v4, v87, v87
	v_pk_mul_f32 v[2:3], v[88:89], v[88:89]
	v_pk_mul_f32 v[0:1], v[90:91], v[90:91]
	v_add_f32_e32 v2, v2, v4
	v_add_f32_e32 v2, v3, v2
	v_add_f32_e32 v0, v0, v2
	v_add_f32_e32 v4, v1, v0
	v_pk_mul_f32 v[2:3], v[92:93], v[92:93]
	v_pk_mul_f32 v[0:1], v[94:95], v[94:95]
	v_add_f32_e32 v2, v2, v4
	v_add_f32_e32 v2, v3, v2
	v_add_f32_e32 v0, v0, v2
	v_and_b32_e32 v2, 64, v195
	v_add_f32_e32 v0, v1, v0
	v_xor_b32_e32 v1, 16, v195
	v_add_u32_e32 v2, 64, v2
	v_cmp_lt_i32_e32 vcc, v1, v2
	s_nop 1
	v_cndmask_b32_e32 v1, v195, v1, vcc
	v_lshlrev_b32_e32 v1, 2, v1
	ds_bpermute_b32 v1, v1, v0
	s_waitcnt lgkmcnt(0)
	v_add_f32_e32 v0, v0, v1
	v_xor_b32_e32 v1, 32, v195
	v_cmp_lt_i32_e32 vcc, v1, v2
	s_nop 1
	v_cndmask_b32_e32 v1, v195, v1, vcc
	v_lshlrev_b32_e32 v1, 2, v1
	ds_bpermute_b32 v1, v1, v0
	s_waitcnt lgkmcnt(0)
	v_add_f32_e32 v0, v0, v1
	v_mul_f32_e32 v1, v16, v16
	v_mul_f32_e32 v0, v1, v0
	v_fmamk_f32 v0, v0, 0x3c800000, v194
	v_mul_f32_e32 v1, 0x4b800000, v0
	v_cmp_gt_f32_e32 vcc, s42, v0
	s_nop 1
	v_cndmask_b32_e32 v0, v0, v1, vcc
	v_rsq_f32_e32 v0, v0
	s_nop 0
	v_mul_f32_e32 v1, 0x45800000, v0
	v_cndmask_b32_e32 v0, v0, v1, vcc
	v_mul_f32_e32 v0, v16, v0
	v_pk_mul_f32 v[18:19], v[80:81], v[0:1] op_sel_hi:[1,0]
	v_pk_mul_f32 v[2:3], v[82:83], v[0:1] op_sel_hi:[1,0]
	v_pk_mul_f32 v[4:5], v[84:85], v[0:1] op_sel_hi:[1,0]
	v_pk_mul_f32 v[6:7], v[86:87], v[0:1] op_sel_hi:[1,0]
	v_pk_mul_f32 v[8:9], v[88:89], v[0:1] op_sel_hi:[1,0]
	v_pk_mul_f32 v[10:11], v[90:91], v[0:1] op_sel_hi:[1,0]
	v_pk_mul_f32 v[12:13], v[92:93], v[0:1] op_sel_hi:[1,0]
	v_pk_mul_f32 v[0:1], v[94:95], v[0:1] op_sel_hi:[1,0]
	v_pk_mul_f32 v[12:13], v[174:175], v[12:13]
	v_pk_mul_f32 v[14:15], v[176:177], v[0:1]
	v_pk_mul_f32 v[10:11], v[172:173], v[10:11]
	v_pk_mul_f32 v[8:9], v[170:171], v[8:9]
	v_pk_mul_f32 v[6:7], v[168:169], v[6:7]
	v_pk_mul_f32 v[4:5], v[166:167], v[4:5]
	v_pk_mul_f32 v[2:3], v[164:165], v[2:3]
	v_pk_mul_f32 v[0:1], v[162:163], v[18:19]
	s_cbranch_execnz .LBB0_578
.LBB0_577:
	v_pk_mul_f32 v[14:15], v[94:95], v[16:17] op_sel_hi:[1,0]
	v_pk_mul_f32 v[10:11], v[90:91], v[16:17] op_sel_hi:[1,0]
	v_pk_mul_f32 v[6:7], v[86:87], v[16:17] op_sel_hi:[1,0]
	v_pk_mul_f32 v[2:3], v[82:83], v[16:17] op_sel_hi:[1,0]
	v_pk_mul_f32 v[12:13], v[92:93], v[16:17] op_sel_hi:[1,0]
	v_pk_mul_f32 v[8:9], v[88:89], v[16:17] op_sel_hi:[1,0]
	v_pk_mul_f32 v[4:5], v[84:85], v[16:17] op_sel_hi:[1,0]
	v_pk_mul_f32 v[0:1], v[80:81], v[16:17] op_sel_hi:[1,0]
.LBB0_578:
	s_and_saveexec_b64 s[4:5], s[70:71]
	s_cbranch_execz .LBB0_580
	s_waitcnt vmcnt(2)
	v_pk_mul_f32 v[16:17], v[8:9], v[204:205]
	v_pk_fma_f32 v[16:17], v[0:1], v[200:201], v[16:17] neg_lo:[0,0,1] neg_hi:[0,0,1]
	v_pk_mul_f32 v[0:1], v[0:1], v[204:205]
	s_nop 0
	v_pk_fma_f32 v[200:201], v[8:9], v[200:201], v[0:1]
	v_pk_mul_f32 v[0:1], v[10:11], v[206:207]
	s_nop 0
	v_pk_fma_f32 v[204:205], v[2:3], v[202:203], v[0:1] neg_lo:[0,0,1] neg_hi:[0,0,1]
	v_pk_mul_f32 v[0:1], v[2:3], v[206:207]
	v_mul_f32_e32 v2, v6, v210
	v_pk_fma_f32 v[202:203], v[10:11], v[202:203], v[0:1]
	v_pk_mul_f32 v[0:1], v[12:13], v[208:209]
	s_nop 0
	v_pk_fma_f32 v[206:207], v[4:5], v[212:213], v[0:1] neg_lo:[0,0,1] neg_hi:[0,0,1]
	v_pk_mul_f32 v[0:1], v[4:5], v[208:209]
	v_pk_mul_f32 v[4:5], v[14:15], v[210:211]
	v_mov_b32_e32 v210, v215
	v_pk_fma_f32 v[22:23], v[6:7], v[214:215], v[4:5] neg_lo:[0,0,1] neg_hi:[0,0,1]
	v_mov_b32_e32 v6, v15
	v_pk_mul_f32 v[4:5], v[6:7], v[210:211]
	v_pk_fma_f32 v[208:209], v[12:13], v[212:213], v[0:1]
	v_mul_f32_e32 v0, v14, v214
	v_mov_b32_e32 v1, v4
	v_mov_b32_e32 v3, v5
	v_pk_add_f32 v[210:211], v[0:1], v[2:3]
	s_nop 0
	v_mov_b64_e32 v[0:1], v[16:17]
	v_mov_b64_e32 v[2:3], v[204:205]
	v_mov_b64_e32 v[4:5], v[206:207]
	v_mov_b64_e32 v[6:7], v[22:23]
	v_mov_b64_e32 v[8:9], v[200:201]
	v_mov_b64_e32 v[10:11], v[202:203]
	v_mov_b64_e32 v[12:13], v[208:209]
	v_mov_b64_e32 v[14:15], v[210:211]
	global_load_dwordx4 v[208:211], v[218:219], off offset:1072
	global_load_dwordx4 v[212:215], v[218:219], off offset:1040
	global_load_dwordx4 v[204:207], v[218:219], off offset:1056
	global_load_dwordx4 v[200:203], v[218:219], off offset:1024
.LBB0_580:
	s_or_b64 exec, exec, s[4:5]
	v_lshlrev_b32_e32 v16, 7, v98
	v_and_b32_e32 v150, 0x3e780, v16
	v_lshl_add_u64 v[16:17], v[96:97], 0, v[150:151]
	v_cvt_pk_bf16_f32 v0, v0, v1
	v_cvt_pk_bf16_f32 v1, v2, v3
	v_cvt_pk_bf16_f32 v2, v4, v5
	v_cvt_pk_bf16_f32 v3, v6, v7
	v_cvt_pk_bf16_f32 v4, v8, v9
	v_cvt_pk_bf16_f32 v5, v10, v11
	v_cvt_pk_bf16_f32 v6, v12, v13
	v_cvt_pk_bf16_f32 v7, v14, v15
	global_store_dwordx4 v[16:17], v[0:3], off
	global_store_dwordx4 v[16:17], v[4:7], off offset:16
.LBB0_581:
	v_or_b32_e32 v80, 16, v98
	v_ashrrev_i32_e32 v81, 31, v80
	v_lshl_add_u64 v[0:1], v[80:81], 2, s[26:27]
	v_mov_b32_e32 v16, v245
	s_and_b64 vcc, exec, s[14:15]
	s_mov_b64 s[4:5], -1
	s_cbranch_vccnz .LBB0_590
	s_and_b64 vcc, exec, s[12:13]
	s_cbranch_vccnz .LBB0_587
	s_and_saveexec_b64 s[4:5], s[6:7]
	s_cbranch_execz .LBB0_586
	v_mul_f32_e32 v0, v64, v16
	v_mul_f32_e32 v0, 0xbfb8aa3b, v0
	v_mul_f32_e32 v1, v65, v16
	v_exp_f32_e32 v0, v0
	v_mul_f32_e32 v1, 0xbfb8aa3b, v1
	v_exp_f32_e32 v1, v1
	v_mul_f32_e32 v3, v67, v16
	v_add_f32_e32 v0, 1.0, v0
	v_rcp_f32_e32 v2, v0
	v_add_f32_e32 v0, 1.0, v1
	v_mul_f32_e32 v1, v66, v16
	v_mul_f32_e32 v1, 0xbfb8aa3b, v1
	v_exp_f32_e32 v1, v1
	v_mul_f32_e32 v3, 0xbfb8aa3b, v3
	v_exp_f32_e32 v5, v3
	v_rcp_f32_e32 v3, v0
	v_add_f32_e32 v0, 1.0, v1
	v_mul_f32_e32 v1, v68, v16
	v_rcp_f32_e32 v4, v0
	v_add_f32_e32 v0, 1.0, v5
	v_mul_f32_e32 v1, 0xbfb8aa3b, v1
	v_mul_f32_e32 v5, v69, v16
	v_exp_f32_e32 v1, v1
	v_mul_f32_e32 v5, 0xbfb8aa3b, v5
	v_exp_f32_e32 v7, v5
	v_rcp_f32_e32 v5, v0
	v_add_f32_e32 v0, 1.0, v1
	v_mul_f32_e32 v1, v70, v16
	v_rcp_f32_e32 v6, v0
	v_add_f32_e32 v0, 1.0, v7
	v_mul_f32_e32 v1, 0xbfb8aa3b, v1
	v_mul_f32_e32 v7, v71, v16
	v_exp_f32_e32 v1, v1
	v_mul_f32_e32 v7, 0xbfb8aa3b, v7
	v_exp_f32_e32 v9, v7
	v_rcp_f32_e32 v7, v0
	v_add_f32_e32 v0, 1.0, v1
	v_rcp_f32_e32 v8, v0
	v_add_f32_e32 v0, 1.0, v9
	v_rcp_f32_e32 v9, v0
	v_lshlrev_b64 v[0:1], 7, v[80:81]
	v_lshl_add_u64 v[0:1], v[154:155], 0, v[0:1]
	global_store_dwordx4 v[0:1], v[2:5], off
	global_store_dwordx4 v[0:1], v[6:9], off offset:16
	s_and_b64 exec, exec, s[8:9]
	s_cbranch_execz .LBB0_586
	v_mul_f32_e32 v2, v72, v16
	v_mul_f32_e32 v3, v73, v16
	v_mul_f32_e32 v4, v74, v16
	v_mul_f32_e32 v5, v75, v16
	v_mul_f32_e32 v2, 0xbfb8aa3b, v2
	v_mul_f32_e32 v3, 0xbfb8aa3b, v3
	v_mul_f32_e32 v4, 0xbfb8aa3b, v4
	v_mul_f32_e32 v5, 0xbfb8aa3b, v5
	v_mul_f32_e32 v6, v76, v16
	v_mul_f32_e32 v7, v77, v16
	v_mul_f32_e32 v8, v78, v16
	v_mul_f32_e32 v9, v79, v16
	v_exp_f32_e32 v2, v2
	v_exp_f32_e32 v3, v3
	v_exp_f32_e32 v4, v4
	v_exp_f32_e32 v5, v5
	v_mul_f32_e32 v6, 0xbfb8aa3b, v6
	v_mul_f32_e32 v7, 0xbfb8aa3b, v7
	v_mul_f32_e32 v8, 0xbfb8aa3b, v8
	v_mul_f32_e32 v9, 0xbfb8aa3b, v9
	v_exp_f32_e32 v6, v6
	v_exp_f32_e32 v7, v7
	v_exp_f32_e32 v8, v8
	v_exp_f32_e32 v9, v9
	v_add_f32_e32 v2, 1.0, v2
	v_add_f32_e32 v3, 1.0, v3
	v_add_f32_e32 v4, 1.0, v4
	v_add_f32_e32 v5, 1.0, v5
	v_rcp_f32_e32 v2, v2
	v_rcp_f32_e32 v3, v3
	v_rcp_f32_e32 v4, v4
	v_rcp_f32_e32 v5, v5
	v_add_f32_e32 v6, 1.0, v6
	v_add_f32_e32 v7, 1.0, v7
	v_add_f32_e32 v8, 1.0, v8
	v_add_f32_e32 v9, 1.0, v9
	v_rcp_f32_e32 v6, v6
	v_rcp_f32_e32 v7, v7
	v_rcp_f32_e32 v8, v8
	v_rcp_f32_e32 v9, v9
	global_store_dwordx4 v[0:1], v[2:5], off offset:32
	global_store_dwordx4 v[0:1], v[6:9], off offset:48

.LBB0_587:
	s_andn2_b64 vcc, exec, s[4:5]
	s_cbranch_vccnz .LBB0_589
	v_mul_f32_e32 v3, 0xbfb8aa3b, v16
	v_mul_f32_e32 v0, v64, v3
	v_exp_f32_e32 v0, v0
	v_mul_f32_e32 v1, v65, v3
	v_exp_f32_e32 v1, v1
	v_mul_f32_e32 v2, v66, v3
	v_fmamk_f32 v0, v0, 0x3b808081, v193
	v_rcp_f32_e32 v0, v0
	v_fmamk_f32 v1, v1, 0x3b808081, v193
	v_rcp_f32_e32 v1, v1
	v_exp_f32_e32 v2, v2
	v_cvt_pk_u8_f32 v0, v0, 0, 0
	v_mul_f32_e32 v4, v68, v3
	v_cvt_pk_u8_f32 v0, v1, 1, v0
	v_fmamk_f32 v1, v2, 0x3b808081, v193
	v_mul_f32_e32 v2, v67, v3
	v_exp_f32_e32 v4, v4
	v_exp_f32_e32 v2, v2
	v_rcp_f32_e32 v1, v1
	v_mul_f32_e32 v5, v69, v3
	v_fmamk_f32 v4, v4, 0x3b808081, v193
	v_fmamk_f32 v2, v2, 0x3b808081, v193
	v_rcp_f32_e32 v4, v4
	v_rcp_f32_e32 v2, v2
	v_exp_f32_e32 v5, v5
	v_cvt_pk_u8_f32 v0, v1, 2, v0
	v_cvt_pk_u8_f32 v1, v4, 0, 0
	v_mul_f32_e32 v4, v70, v3
	v_cvt_pk_u8_f32 v0, v2, 3, v0
	v_fmamk_f32 v2, v5, 0x3b808081, v193
	v_exp_f32_e32 v4, v4
	v_mul_f32_e32 v5, v71, v3
	v_exp_f32_e32 v5, v5
	v_rcp_f32_e32 v2, v2
	v_fmamk_f32 v4, v4, 0x3b808081, v193
	v_rcp_f32_e32 v4, v4
	v_fmamk_f32 v5, v5, 0x3b808081, v193
	v_rcp_f32_e32 v5, v5
	v_mul_f32_e32 v6, v72, v3
	v_cvt_pk_u8_f32 v1, v2, 1, v1
	v_exp_f32_e32 v6, v6
	v_cvt_pk_u8_f32 v1, v4, 2, v1
	v_mul_f32_e32 v4, v73, v3
	v_cvt_pk_u8_f32 v1, v5, 3, v1
	v_exp_f32_e32 v4, v4
	v_mul_f32_e32 v5, v74, v3
	v_exp_f32_e32 v5, v5
	v_fmamk_f32 v2, v6, 0x3b808081, v193
	v_rcp_f32_e32 v2, v2
	v_fmamk_f32 v4, v4, 0x3b808081, v193
	v_rcp_f32_e32 v4, v4
	v_fmamk_f32 v5, v5, 0x3b808081, v193
	v_mul_f32_e32 v6, v75, v3
	v_rcp_f32_e32 v5, v5
	v_exp_f32_e32 v6, v6
	v_cvt_pk_u8_f32 v2, v2, 0, 0
	v_cvt_pk_u8_f32 v2, v4, 1, v2
	v_cvt_pk_u8_f32 v2, v5, 2, v2
	v_fmamk_f32 v4, v6, 0x3b808081, v193
	v_mul_f32_e32 v5, v76, v3
	v_mul_f32_e32 v6, v77, v3
	v_rcp_f32_e32 v4, v4
	v_exp_f32_e32 v5, v5
	v_exp_f32_e32 v6, v6
	v_cvt_pk_u8_f32 v2, v4, 3, v2
	v_fmamk_f32 v4, v5, 0x3b808081, v193
	v_fmamk_f32 v5, v6, 0x3b808081, v193
	v_mul_f32_e32 v6, v78, v3
	v_exp_f32_e32 v6, v6
	v_mul_f32_e32 v3, v79, v3
	v_exp_f32_e32 v3, v3
	v_rcp_f32_e32 v4, v4
	v_rcp_f32_e32 v5, v5
	v_fmamk_f32 v6, v6, 0x3b808081, v193
	v_rcp_f32_e32 v6, v6
	v_fmamk_f32 v3, v3, 0x3b808081, v193
	v_rcp_f32_e32 v3, v3
	v_cvt_pk_u8_f32 v4, v4, 0, 0
	v_cvt_pk_u8_f32 v4, v5, 1, v4
	v_cvt_pk_u8_f32 v4, v6, 2, v4
	v_cvt_pk_u8_f32 v3, v3, 3, v4
	v_lshlrev_b64 v[4:5], 10, v[80:81]
	v_lshl_add_u64 v[4:5], v[178:179], 0, v[4:5]
	global_store_dwordx4 v[4:5], v[0:3], off

.LBB0_590:
	s_andn2_b64 vcc, exec, s[4:5]
	s_cbranch_vccnz .LBB0_597
	s_and_b64 vcc, exec, s[10:11]
	s_cbranch_vccnz .LBB0_637
	v_mul_f32_e32 v4, v65, v65
	v_fmac_f32_e32 v4, v64, v64
	v_fmac_f32_e32 v4, v66, v66
	v_fmac_f32_e32 v4, v67, v67
	v_fmac_f32_e32 v4, v68, v68
	v_fmac_f32_e32 v4, v69, v69
	v_fmac_f32_e32 v4, v70, v70
	v_fmac_f32_e32 v4, v71, v71
	v_pk_mul_f32 v[2:3], v[72:73], v[72:73]
	v_pk_mul_f32 v[0:1], v[74:75], v[74:75]
	v_add_f32_e32 v2, v2, v4
	v_add_f32_e32 v2, v3, v2
	v_add_f32_e32 v0, v0, v2
	v_add_f32_e32 v4, v1, v0
	v_pk_mul_f32 v[2:3], v[76:77], v[76:77]
	v_pk_mul_f32 v[0:1], v[78:79], v[78:79]
	v_add_f32_e32 v2, v2, v4
	v_add_f32_e32 v2, v3, v2
	v_add_f32_e32 v0, v0, v2
	v_and_b32_e32 v2, 64, v195
	v_add_f32_e32 v0, v1, v0
	v_xor_b32_e32 v1, 16, v195
	v_add_u32_e32 v2, 64, v2
	v_cmp_lt_i32_e32 vcc, v1, v2
	s_nop 1
	v_cndmask_b32_e32 v1, v195, v1, vcc
	v_lshlrev_b32_e32 v1, 2, v1
	ds_bpermute_b32 v1, v1, v0
	s_waitcnt lgkmcnt(0)
	v_add_f32_e32 v0, v0, v1
	v_xor_b32_e32 v1, 32, v195
	v_cmp_lt_i32_e32 vcc, v1, v2
	s_nop 1
	v_cndmask_b32_e32 v1, v195, v1, vcc
	v_lshlrev_b32_e32 v1, 2, v1
	ds_bpermute_b32 v1, v1, v0
	s_waitcnt lgkmcnt(0)
	v_add_f32_e32 v0, v0, v1
	v_mul_f32_e32 v1, v16, v16
	v_mul_f32_e32 v0, v1, v0
	v_fmamk_f32 v0, v0, 0x3c800000, v194
	v_mul_f32_e32 v1, 0x4b800000, v0
	v_cmp_gt_f32_e32 vcc, s42, v0
	s_nop 1
	v_cndmask_b32_e32 v0, v0, v1, vcc
	v_rsq_f32_e32 v0, v0
	s_nop 0
	v_mul_f32_e32 v1, 0x45800000, v0
	v_cndmask_b32_e32 v0, v0, v1, vcc
	v_mul_f32_e32 v0, v16, v0
	v_pk_mul_f32 v[18:19], v[64:65], v[0:1] op_sel_hi:[1,0]
	v_pk_mul_f32 v[2:3], v[66:67], v[0:1] op_sel_hi:[1,0]
	v_pk_mul_f32 v[4:5], v[68:69], v[0:1] op_sel_hi:[1,0]
	v_pk_mul_f32 v[6:7], v[70:71], v[0:1] op_sel_hi:[1,0]
	v_pk_mul_f32 v[8:9], v[72:73], v[0:1] op_sel_hi:[1,0]
	v_pk_mul_f32 v[10:11], v[74:75], v[0:1] op_sel_hi:[1,0]
	v_pk_mul_f32 v[12:13], v[76:77], v[0:1] op_sel_hi:[1,0]
	v_pk_mul_f32 v[0:1], v[78:79], v[0:1] op_sel_hi:[1,0]
	v_pk_mul_f32 v[12:13], v[174:175], v[12:13]
	v_pk_mul_f32 v[14:15], v[176:177], v[0:1]
	v_pk_mul_f32 v[10:11], v[172:173], v[10:11]
	v_pk_mul_f32 v[8:9], v[170:171], v[8:9]
	v_pk_mul_f32 v[6:7], v[168:169], v[6:7]
	v_pk_mul_f32 v[4:5], v[166:167], v[4:5]
	v_pk_mul_f32 v[2:3], v[164:165], v[2:3]
	v_pk_mul_f32 v[0:1], v[162:163], v[18:19]
	s_cbranch_execnz .LBB0_594
.LBB0_593:
	v_pk_mul_f32 v[14:15], v[78:79], v[16:17] op_sel_hi:[1,0]
	v_pk_mul_f32 v[10:11], v[74:75], v[16:17] op_sel_hi:[1,0]
	v_pk_mul_f32 v[6:7], v[70:71], v[16:17] op_sel_hi:[1,0]
	v_pk_mul_f32 v[2:3], v[66:67], v[16:17] op_sel_hi:[1,0]
	v_pk_mul_f32 v[12:13], v[76:77], v[16:17] op_sel_hi:[1,0]
	v_pk_mul_f32 v[8:9], v[72:73], v[16:17] op_sel_hi:[1,0]
	v_pk_mul_f32 v[4:5], v[68:69], v[16:17] op_sel_hi:[1,0]
	v_pk_mul_f32 v[0:1], v[64:65], v[16:17] op_sel_hi:[1,0]
.LBB0_594:
	s_and_saveexec_b64 s[4:5], s[70:71]
	s_cbranch_execz .LBB0_596
	s_waitcnt vmcnt(2)
	v_pk_mul_f32 v[16:17], v[8:9], v[204:205]
	v_pk_fma_f32 v[16:17], v[0:1], v[200:201], v[16:17] neg_lo:[0,0,1] neg_hi:[0,0,1]
	v_pk_mul_f32 v[0:1], v[0:1], v[204:205]
	s_nop 0
	v_pk_fma_f32 v[200:201], v[8:9], v[200:201], v[0:1]
	v_pk_mul_f32 v[0:1], v[10:11], v[206:207]
	s_nop 0
	v_pk_fma_f32 v[204:205], v[2:3], v[202:203], v[0:1] neg_lo:[0,0,1] neg_hi:[0,0,1]
	v_pk_mul_f32 v[0:1], v[2:3], v[206:207]
	v_mul_f32_e32 v2, v6, v210
	v_pk_fma_f32 v[202:203], v[10:11], v[202:203], v[0:1]
	v_pk_mul_f32 v[0:1], v[12:13], v[208:209]
	s_nop 0
	v_pk_fma_f32 v[206:207], v[4:5], v[212:213], v[0:1] neg_lo:[0,0,1] neg_hi:[0,0,1]
	v_pk_mul_f32 v[0:1], v[4:5], v[208:209]
	v_pk_mul_f32 v[4:5], v[14:15], v[210:211]
	v_mov_b32_e32 v210, v215
	v_pk_fma_f32 v[22:23], v[6:7], v[214:215], v[4:5] neg_lo:[0,0,1] neg_hi:[0,0,1]
	v_mov_b32_e32 v6, v15
	v_pk_mul_f32 v[4:5], v[6:7], v[210:211]
	v_pk_fma_f32 v[208:209], v[12:13], v[212:213], v[0:1]
	v_mul_f32_e32 v0, v14, v214
	v_mov_b32_e32 v1, v4
	v_mov_b32_e32 v3, v5
	v_pk_add_f32 v[210:211], v[0:1], v[2:3]
	s_nop 0
	v_mov_b64_e32 v[0:1], v[16:17]
	v_mov_b64_e32 v[2:3], v[204:205]
	v_mov_b64_e32 v[4:5], v[206:207]
	v_mov_b64_e32 v[6:7], v[22:23]
	v_mov_b64_e32 v[8:9], v[200:201]
	v_mov_b64_e32 v[10:11], v[202:203]
	v_mov_b64_e32 v[12:13], v[208:209]
	v_mov_b64_e32 v[14:15], v[210:211]
	global_load_dwordx4 v[208:211], v[218:219], off offset:2096
	global_load_dwordx4 v[212:215], v[218:219], off offset:2064
	global_load_dwordx4 v[204:207], v[218:219], off offset:2080
	global_load_dwordx4 v[200:203], v[218:219], off offset:2048
.LBB0_596:
	s_or_b64 exec, exec, s[4:5]
	v_lshlrev_b32_e32 v16, 7, v80
	v_and_b32_e32 v150, 0x3ff80, v16
	v_lshl_add_u64 v[16:17], v[96:97], 0, v[150:151]
	v_cvt_pk_bf16_f32 v0, v0, v1
	v_cvt_pk_bf16_f32 v1, v2, v3
	v_cvt_pk_bf16_f32 v2, v4, v5
	v_cvt_pk_bf16_f32 v3, v6, v7
	v_cvt_pk_bf16_f32 v4, v8, v9
	v_cvt_pk_bf16_f32 v5, v10, v11
	v_cvt_pk_bf16_f32 v6, v12, v13
	v_cvt_pk_bf16_f32 v7, v14, v15
	global_store_dwordx4 v[16:17], v[0:3], off
	global_store_dwordx4 v[16:17], v[4:7], off offset:16
.LBB0_597:
	v_or_b32_e32 v64, 32, v98
	v_ashrrev_i32_e32 v65, 31, v64
	v_lshl_add_u64 v[0:1], v[64:65], 2, s[26:27]
	v_mov_b32_e32 v16, v246
	s_and_b64 vcc, exec, s[14:15]
	s_mov_b64 s[4:5], -1
	s_cbranch_vccnz .LBB0_606
	s_and_b64 vcc, exec, s[12:13]
	s_cbranch_vccnz .LBB0_603
	s_and_saveexec_b64 s[4:5], s[6:7]
	s_cbranch_execz .LBB0_602
	v_mul_f32_e32 v0, v48, v16
	v_mul_f32_e32 v0, 0xbfb8aa3b, v0
	v_mul_f32_e32 v1, v49, v16
	v_exp_f32_e32 v0, v0
	v_mul_f32_e32 v1, 0xbfb8aa3b, v1
	v_exp_f32_e32 v1, v1
	v_mul_f32_e32 v3, v51, v16
	v_add_f32_e32 v0, 1.0, v0
	v_rcp_f32_e32 v2, v0
	v_add_f32_e32 v0, 1.0, v1
	v_mul_f32_e32 v1, v50, v16
	v_mul_f32_e32 v1, 0xbfb8aa3b, v1
	v_exp_f32_e32 v1, v1
	v_mul_f32_e32 v3, 0xbfb8aa3b, v3
	v_exp_f32_e32 v5, v3
	v_rcp_f32_e32 v3, v0
	v_add_f32_e32 v0, 1.0, v1
	v_mul_f32_e32 v1, v52, v16
	v_rcp_f32_e32 v4, v0
	v_add_f32_e32 v0, 1.0, v5
	v_mul_f32_e32 v1, 0xbfb8aa3b, v1
	v_mul_f32_e32 v5, v53, v16
	v_exp_f32_e32 v1, v1
	v_mul_f32_e32 v5, 0xbfb8aa3b, v5
	v_exp_f32_e32 v7, v5
	v_rcp_f32_e32 v5, v0
	v_add_f32_e32 v0, 1.0, v1
	v_mul_f32_e32 v1, v54, v16
	v_rcp_f32_e32 v6, v0
	v_add_f32_e32 v0, 1.0, v7
	v_mul_f32_e32 v1, 0xbfb8aa3b, v1
	v_mul_f32_e32 v7, v55, v16
	v_exp_f32_e32 v1, v1
	v_mul_f32_e32 v7, 0xbfb8aa3b, v7
	v_exp_f32_e32 v9, v7
	v_rcp_f32_e32 v7, v0
	v_add_f32_e32 v0, 1.0, v1
	v_rcp_f32_e32 v8, v0
	v_add_f32_e32 v0, 1.0, v9
	v_rcp_f32_e32 v9, v0
	v_lshlrev_b64 v[0:1], 7, v[64:65]
	v_lshl_add_u64 v[0:1], v[154:155], 0, v[0:1]
	global_store_dwordx4 v[0:1], v[2:5], off
	global_store_dwordx4 v[0:1], v[6:9], off offset:16
	s_and_b64 exec, exec, s[8:9]
	s_cbranch_execz .LBB0_602
	v_mul_f32_e32 v2, v56, v16
	v_mul_f32_e32 v3, v57, v16
	v_mul_f32_e32 v4, v58, v16
	v_mul_f32_e32 v5, v59, v16
	v_mul_f32_e32 v2, 0xbfb8aa3b, v2
	v_mul_f32_e32 v3, 0xbfb8aa3b, v3
	v_mul_f32_e32 v4, 0xbfb8aa3b, v4
	v_mul_f32_e32 v5, 0xbfb8aa3b, v5
	v_mul_f32_e32 v6, v60, v16
	v_mul_f32_e32 v7, v61, v16
	v_mul_f32_e32 v8, v62, v16
	v_mul_f32_e32 v9, v63, v16
	v_exp_f32_e32 v2, v2
	v_exp_f32_e32 v3, v3
	v_exp_f32_e32 v4, v4
	v_exp_f32_e32 v5, v5
	v_mul_f32_e32 v6, 0xbfb8aa3b, v6
	v_mul_f32_e32 v7, 0xbfb8aa3b, v7
	v_mul_f32_e32 v8, 0xbfb8aa3b, v8
	v_mul_f32_e32 v9, 0xbfb8aa3b, v9
	v_exp_f32_e32 v6, v6
	v_exp_f32_e32 v7, v7
	v_exp_f32_e32 v8, v8
	v_exp_f32_e32 v9, v9
	v_add_f32_e32 v2, 1.0, v2
	v_add_f32_e32 v3, 1.0, v3
	v_add_f32_e32 v4, 1.0, v4
	v_add_f32_e32 v5, 1.0, v5
	v_rcp_f32_e32 v2, v2
	v_rcp_f32_e32 v3, v3
	v_rcp_f32_e32 v4, v4
	v_rcp_f32_e32 v5, v5
	v_add_f32_e32 v6, 1.0, v6
	v_add_f32_e32 v7, 1.0, v7
	v_add_f32_e32 v8, 1.0, v8
	v_add_f32_e32 v9, 1.0, v9
	v_rcp_f32_e32 v6, v6
	v_rcp_f32_e32 v7, v7
	v_rcp_f32_e32 v8, v8
	v_rcp_f32_e32 v9, v9
	global_store_dwordx4 v[0:1], v[2:5], off offset:32
	global_store_dwordx4 v[0:1], v[6:9], off offset:48

.LBB0_603:
	s_andn2_b64 vcc, exec, s[4:5]
	s_cbranch_vccnz .LBB0_605
	v_mul_f32_e32 v3, 0xbfb8aa3b, v16
	v_mul_f32_e32 v0, v48, v3
	v_exp_f32_e32 v0, v0
	v_mul_f32_e32 v1, v49, v3
	v_exp_f32_e32 v1, v1
	v_mul_f32_e32 v2, v50, v3
	v_fmamk_f32 v0, v0, 0x3b808081, v193
	v_rcp_f32_e32 v0, v0
	v_fmamk_f32 v1, v1, 0x3b808081, v193
	v_rcp_f32_e32 v1, v1
	v_exp_f32_e32 v2, v2
	v_cvt_pk_u8_f32 v0, v0, 0, 0
	v_mul_f32_e32 v4, v52, v3
	v_cvt_pk_u8_f32 v0, v1, 1, v0
	v_fmamk_f32 v1, v2, 0x3b808081, v193
	v_mul_f32_e32 v2, v51, v3
	v_exp_f32_e32 v4, v4
	v_exp_f32_e32 v2, v2
	v_rcp_f32_e32 v1, v1
	v_mul_f32_e32 v5, v53, v3
	v_fmamk_f32 v4, v4, 0x3b808081, v193
	v_fmamk_f32 v2, v2, 0x3b808081, v193
	v_rcp_f32_e32 v4, v4
	v_rcp_f32_e32 v2, v2
	v_exp_f32_e32 v5, v5
	v_cvt_pk_u8_f32 v0, v1, 2, v0
	v_cvt_pk_u8_f32 v1, v4, 0, 0
	v_mul_f32_e32 v4, v54, v3
	v_cvt_pk_u8_f32 v0, v2, 3, v0
	v_fmamk_f32 v2, v5, 0x3b808081, v193
	v_exp_f32_e32 v4, v4
	v_mul_f32_e32 v5, v55, v3
	v_exp_f32_e32 v5, v5
	v_rcp_f32_e32 v2, v2
	v_fmamk_f32 v4, v4, 0x3b808081, v193
	v_rcp_f32_e32 v4, v4
	v_fmamk_f32 v5, v5, 0x3b808081, v193
	v_rcp_f32_e32 v5, v5
	v_mul_f32_e32 v6, v56, v3
	v_cvt_pk_u8_f32 v1, v2, 1, v1
	v_exp_f32_e32 v6, v6
	v_cvt_pk_u8_f32 v1, v4, 2, v1
	v_mul_f32_e32 v4, v57, v3
	v_cvt_pk_u8_f32 v1, v5, 3, v1
	v_exp_f32_e32 v4, v4
	v_mul_f32_e32 v5, v58, v3
	v_exp_f32_e32 v5, v5
	v_fmamk_f32 v2, v6, 0x3b808081, v193
	v_rcp_f32_e32 v2, v2
	v_fmamk_f32 v4, v4, 0x3b808081, v193
	v_rcp_f32_e32 v4, v4
	v_fmamk_f32 v5, v5, 0x3b808081, v193
	v_mul_f32_e32 v6, v59, v3
	v_rcp_f32_e32 v5, v5
	v_exp_f32_e32 v6, v6
	v_cvt_pk_u8_f32 v2, v2, 0, 0
	v_cvt_pk_u8_f32 v2, v4, 1, v2
	v_cvt_pk_u8_f32 v2, v5, 2, v2
	v_fmamk_f32 v4, v6, 0x3b808081, v193
	v_mul_f32_e32 v5, v60, v3
	v_mul_f32_e32 v6, v61, v3
	v_rcp_f32_e32 v4, v4
	v_exp_f32_e32 v5, v5
	v_exp_f32_e32 v6, v6
	v_cvt_pk_u8_f32 v2, v4, 3, v2
	v_fmamk_f32 v4, v5, 0x3b808081, v193
	v_fmamk_f32 v5, v6, 0x3b808081, v193
	v_mul_f32_e32 v6, v62, v3
	v_exp_f32_e32 v6, v6
	v_mul_f32_e32 v3, v63, v3
	v_exp_f32_e32 v3, v3
	v_rcp_f32_e32 v4, v4
	v_rcp_f32_e32 v5, v5
	v_fmamk_f32 v6, v6, 0x3b808081, v193
	v_rcp_f32_e32 v6, v6
	v_fmamk_f32 v3, v3, 0x3b808081, v193
	v_rcp_f32_e32 v3, v3
	v_cvt_pk_u8_f32 v4, v4, 0, 0
	v_cvt_pk_u8_f32 v4, v5, 1, v4
	v_cvt_pk_u8_f32 v4, v6, 2, v4
	v_cvt_pk_u8_f32 v3, v3, 3, v4
	v_lshlrev_b64 v[4:5], 10, v[64:65]
	v_lshl_add_u64 v[4:5], v[178:179], 0, v[4:5]
	global_store_dwordx4 v[4:5], v[0:3], off

.LBB0_606:
	s_andn2_b64 vcc, exec, s[4:5]
	s_cbranch_vccnz .LBB0_613
	s_and_b64 vcc, exec, s[10:11]
	s_cbranch_vccnz .LBB0_638
	v_mul_f32_e32 v4, v49, v49
	v_fmac_f32_e32 v4, v48, v48
	v_fmac_f32_e32 v4, v50, v50
	v_fmac_f32_e32 v4, v51, v51
	v_fmac_f32_e32 v4, v52, v52
	v_fmac_f32_e32 v4, v53, v53
	v_fmac_f32_e32 v4, v54, v54
	v_fmac_f32_e32 v4, v55, v55
	v_pk_mul_f32 v[2:3], v[56:57], v[56:57]
	v_pk_mul_f32 v[0:1], v[58:59], v[58:59]
	v_add_f32_e32 v2, v2, v4
	v_add_f32_e32 v2, v3, v2
	v_add_f32_e32 v0, v0, v2
	v_add_f32_e32 v4, v1, v0
	v_pk_mul_f32 v[2:3], v[60:61], v[60:61]
	v_pk_mul_f32 v[0:1], v[62:63], v[62:63]
	v_add_f32_e32 v2, v2, v4
	v_add_f32_e32 v2, v3, v2
	v_add_f32_e32 v0, v0, v2
	v_and_b32_e32 v2, 64, v195
	v_add_f32_e32 v0, v1, v0
	v_xor_b32_e32 v1, 16, v195
	v_add_u32_e32 v2, 64, v2
	v_cmp_lt_i32_e32 vcc, v1, v2
	s_nop 1
	v_cndmask_b32_e32 v1, v195, v1, vcc
	v_lshlrev_b32_e32 v1, 2, v1
	ds_bpermute_b32 v1, v1, v0
	s_waitcnt lgkmcnt(0)
	v_add_f32_e32 v0, v0, v1
	v_xor_b32_e32 v1, 32, v195
	v_cmp_lt_i32_e32 vcc, v1, v2
	s_nop 1
	v_cndmask_b32_e32 v1, v195, v1, vcc
	v_lshlrev_b32_e32 v1, 2, v1
	ds_bpermute_b32 v1, v1, v0
	s_waitcnt lgkmcnt(0)
	v_add_f32_e32 v0, v0, v1
	v_mul_f32_e32 v1, v16, v16
	v_mul_f32_e32 v0, v1, v0
	v_fmamk_f32 v0, v0, 0x3c800000, v194
	v_mul_f32_e32 v1, 0x4b800000, v0
	v_cmp_gt_f32_e32 vcc, s42, v0
	s_nop 1
	v_cndmask_b32_e32 v0, v0, v1, vcc
	v_rsq_f32_e32 v0, v0
	s_nop 0
	v_mul_f32_e32 v1, 0x45800000, v0
	v_cndmask_b32_e32 v0, v0, v1, vcc
	v_mul_f32_e32 v0, v16, v0
	v_pk_mul_f32 v[18:19], v[48:49], v[0:1] op_sel_hi:[1,0]
	v_pk_mul_f32 v[2:3], v[50:51], v[0:1] op_sel_hi:[1,0]
	v_pk_mul_f32 v[4:5], v[52:53], v[0:1] op_sel_hi:[1,0]
	v_pk_mul_f32 v[6:7], v[54:55], v[0:1] op_sel_hi:[1,0]
	v_pk_mul_f32 v[8:9], v[56:57], v[0:1] op_sel_hi:[1,0]
	v_pk_mul_f32 v[10:11], v[58:59], v[0:1] op_sel_hi:[1,0]
	v_pk_mul_f32 v[12:13], v[60:61], v[0:1] op_sel_hi:[1,0]
	v_pk_mul_f32 v[0:1], v[62:63], v[0:1] op_sel_hi:[1,0]
	v_pk_mul_f32 v[12:13], v[174:175], v[12:13]
	v_pk_mul_f32 v[14:15], v[176:177], v[0:1]
	v_pk_mul_f32 v[10:11], v[172:173], v[10:11]
	v_pk_mul_f32 v[8:9], v[170:171], v[8:9]
	v_pk_mul_f32 v[6:7], v[168:169], v[6:7]
	v_pk_mul_f32 v[4:5], v[166:167], v[4:5]
	v_pk_mul_f32 v[2:3], v[164:165], v[2:3]
	v_pk_mul_f32 v[0:1], v[162:163], v[18:19]
	s_cbranch_execnz .LBB0_610
.LBB0_609:
	v_pk_mul_f32 v[14:15], v[62:63], v[16:17] op_sel_hi:[1,0]
	v_pk_mul_f32 v[10:11], v[58:59], v[16:17] op_sel_hi:[1,0]
	v_pk_mul_f32 v[6:7], v[54:55], v[16:17] op_sel_hi:[1,0]
	v_pk_mul_f32 v[2:3], v[50:51], v[16:17] op_sel_hi:[1,0]
	v_pk_mul_f32 v[12:13], v[60:61], v[16:17] op_sel_hi:[1,0]
	v_pk_mul_f32 v[8:9], v[56:57], v[16:17] op_sel_hi:[1,0]
	v_pk_mul_f32 v[4:5], v[52:53], v[16:17] op_sel_hi:[1,0]
	v_pk_mul_f32 v[0:1], v[48:49], v[16:17] op_sel_hi:[1,0]
.LBB0_610:
	s_and_saveexec_b64 s[4:5], s[70:71]
	s_cbranch_execz .LBB0_612
	s_waitcnt vmcnt(2)
	v_pk_mul_f32 v[16:17], v[8:9], v[204:205]
	v_pk_fma_f32 v[16:17], v[0:1], v[200:201], v[16:17] neg_lo:[0,0,1] neg_hi:[0,0,1]
	v_pk_mul_f32 v[0:1], v[0:1], v[204:205]
	s_nop 0
	v_pk_fma_f32 v[200:201], v[8:9], v[200:201], v[0:1]
	v_pk_mul_f32 v[0:1], v[10:11], v[206:207]
	s_nop 0
	v_pk_fma_f32 v[204:205], v[2:3], v[202:203], v[0:1] neg_lo:[0,0,1] neg_hi:[0,0,1]
	v_pk_mul_f32 v[0:1], v[2:3], v[206:207]
	v_mul_f32_e32 v2, v6, v210
	v_pk_fma_f32 v[202:203], v[10:11], v[202:203], v[0:1]
	v_pk_mul_f32 v[0:1], v[12:13], v[208:209]
	s_nop 0
	v_pk_fma_f32 v[206:207], v[4:5], v[212:213], v[0:1] neg_lo:[0,0,1] neg_hi:[0,0,1]
	v_pk_mul_f32 v[0:1], v[4:5], v[208:209]
	v_pk_mul_f32 v[4:5], v[14:15], v[210:211]
	v_mov_b32_e32 v210, v215
	v_pk_fma_f32 v[22:23], v[6:7], v[214:215], v[4:5] neg_lo:[0,0,1] neg_hi:[0,0,1]
	v_mov_b32_e32 v6, v15
	v_pk_mul_f32 v[4:5], v[6:7], v[210:211]
	v_pk_fma_f32 v[208:209], v[12:13], v[212:213], v[0:1]
	v_mul_f32_e32 v0, v14, v214
	v_mov_b32_e32 v1, v4
	v_mov_b32_e32 v3, v5
	v_pk_add_f32 v[210:211], v[0:1], v[2:3]
	s_nop 0
	v_mov_b64_e32 v[0:1], v[16:17]
	v_mov_b64_e32 v[2:3], v[204:205]
	v_mov_b64_e32 v[4:5], v[206:207]
	v_mov_b64_e32 v[6:7], v[22:23]
	v_mov_b64_e32 v[8:9], v[200:201]
	v_mov_b64_e32 v[10:11], v[202:203]
	v_mov_b64_e32 v[12:13], v[208:209]
	v_mov_b64_e32 v[14:15], v[210:211]
	global_load_dwordx4 v[208:211], v[218:219], off offset:3120
	global_load_dwordx4 v[212:215], v[218:219], off offset:3088
	global_load_dwordx4 v[204:207], v[218:219], off offset:3104
	global_load_dwordx4 v[200:203], v[218:219], off offset:3072
.LBB0_612:
	s_or_b64 exec, exec, s[4:5]
	v_lshlrev_b32_e32 v16, 7, v64
	v_and_b32_e32 v150, 0x3ff80, v16
	v_lshl_add_u64 v[16:17], v[96:97], 0, v[150:151]
	v_cvt_pk_bf16_f32 v0, v0, v1
	v_cvt_pk_bf16_f32 v1, v2, v3
	v_cvt_pk_bf16_f32 v2, v4, v5
	v_cvt_pk_bf16_f32 v3, v6, v7
	v_cvt_pk_bf16_f32 v4, v8, v9
	v_cvt_pk_bf16_f32 v5, v10, v11
	v_cvt_pk_bf16_f32 v6, v12, v13
	v_cvt_pk_bf16_f32 v7, v14, v15
	global_store_dwordx4 v[16:17], v[0:3], off
	global_store_dwordx4 v[16:17], v[4:7], off offset:16
.LBB0_613:
	v_or_b32_e32 v48, 48, v98
	v_ashrrev_i32_e32 v49, 31, v48
	v_lshl_add_u64 v[0:1], v[48:49], 2, s[26:27]
	v_mov_b32_e32 v16, v247
	s_and_b64 vcc, exec, s[14:15]
	s_mov_b64 s[4:5], -1
	s_cbranch_vccnz .LBB0_622
	s_and_b64 vcc, exec, s[12:13]
	s_cbranch_vccnz .LBB0_619
	s_and_saveexec_b64 s[4:5], s[6:7]
	s_cbranch_execz .LBB0_618
	v_mul_f32_e32 v0, v36, v16
	v_mul_f32_e32 v0, 0xbfb8aa3b, v0
	v_mul_f32_e32 v1, v37, v16
	v_exp_f32_e32 v0, v0
	v_mul_f32_e32 v1, 0xbfb8aa3b, v1
	v_exp_f32_e32 v1, v1
	v_mul_f32_e32 v3, v39, v16
	v_add_f32_e32 v0, 1.0, v0
	v_rcp_f32_e32 v2, v0
	v_add_f32_e32 v0, 1.0, v1
	v_mul_f32_e32 v1, v38, v16
	v_mul_f32_e32 v1, 0xbfb8aa3b, v1
	v_exp_f32_e32 v1, v1
	v_mul_f32_e32 v3, 0xbfb8aa3b, v3
	v_exp_f32_e32 v5, v3
	v_rcp_f32_e32 v3, v0
	v_add_f32_e32 v0, 1.0, v1
	v_mul_f32_e32 v1, v40, v16
	v_rcp_f32_e32 v4, v0
	v_add_f32_e32 v0, 1.0, v5
	v_mul_f32_e32 v1, 0xbfb8aa3b, v1
	v_mul_f32_e32 v5, v41, v16
	v_exp_f32_e32 v1, v1
	v_mul_f32_e32 v5, 0xbfb8aa3b, v5
	v_exp_f32_e32 v7, v5
	v_rcp_f32_e32 v5, v0
	v_add_f32_e32 v0, 1.0, v1
	v_mul_f32_e32 v1, v42, v16
	v_rcp_f32_e32 v6, v0
	v_add_f32_e32 v0, 1.0, v7
	v_mul_f32_e32 v1, 0xbfb8aa3b, v1
	v_mul_f32_e32 v7, v43, v16
	v_exp_f32_e32 v1, v1
	v_mul_f32_e32 v7, 0xbfb8aa3b, v7
	v_exp_f32_e32 v9, v7
	v_rcp_f32_e32 v7, v0
	v_add_f32_e32 v0, 1.0, v1
	v_rcp_f32_e32 v8, v0
	v_add_f32_e32 v0, 1.0, v9
	v_rcp_f32_e32 v9, v0
	v_lshlrev_b64 v[0:1], 7, v[48:49]
	v_lshl_add_u64 v[0:1], v[154:155], 0, v[0:1]
	global_store_dwordx4 v[0:1], v[2:5], off
	global_store_dwordx4 v[0:1], v[6:9], off offset:16
	s_and_b64 exec, exec, s[8:9]
	s_cbranch_execz .LBB0_618
	v_mul_f32_e32 v2, v44, v16
	v_mul_f32_e32 v3, v45, v16
	v_mul_f32_e32 v4, v46, v16
	v_mul_f32_e32 v5, v47, v16
	v_mul_f32_e32 v2, 0xbfb8aa3b, v2
	v_mul_f32_e32 v3, 0xbfb8aa3b, v3
	v_mul_f32_e32 v4, 0xbfb8aa3b, v4
	v_mul_f32_e32 v5, 0xbfb8aa3b, v5
	v_mul_f32_e32 v6, v32, v16
	v_mul_f32_e32 v7, v33, v16
	v_mul_f32_e32 v8, v34, v16
	v_mul_f32_e32 v9, v35, v16
	v_exp_f32_e32 v2, v2
	v_exp_f32_e32 v3, v3
	v_exp_f32_e32 v4, v4
	v_exp_f32_e32 v5, v5
	v_mul_f32_e32 v6, 0xbfb8aa3b, v6
	v_mul_f32_e32 v7, 0xbfb8aa3b, v7
	v_mul_f32_e32 v8, 0xbfb8aa3b, v8
	v_mul_f32_e32 v9, 0xbfb8aa3b, v9
	v_exp_f32_e32 v6, v6
	v_exp_f32_e32 v7, v7
	v_exp_f32_e32 v8, v8
	v_exp_f32_e32 v9, v9
	v_add_f32_e32 v2, 1.0, v2
	v_add_f32_e32 v3, 1.0, v3
	v_add_f32_e32 v4, 1.0, v4
	v_add_f32_e32 v5, 1.0, v5
	v_rcp_f32_e32 v2, v2
	v_rcp_f32_e32 v3, v3
	v_rcp_f32_e32 v4, v4
	v_rcp_f32_e32 v5, v5
	v_add_f32_e32 v6, 1.0, v6
	v_add_f32_e32 v7, 1.0, v7
	v_add_f32_e32 v8, 1.0, v8
	v_add_f32_e32 v9, 1.0, v9
	v_rcp_f32_e32 v6, v6
	v_rcp_f32_e32 v7, v7
	v_rcp_f32_e32 v8, v8
	v_rcp_f32_e32 v9, v9
	global_store_dwordx4 v[0:1], v[2:5], off offset:32
	global_store_dwordx4 v[0:1], v[6:9], off offset:48

.LBB0_619:
	s_andn2_b64 vcc, exec, s[4:5]
	s_cbranch_vccnz .LBB0_621
	v_mul_f32_e32 v3, 0xbfb8aa3b, v16
	v_mul_f32_e32 v0, v36, v3
	v_exp_f32_e32 v0, v0
	v_mul_f32_e32 v1, v37, v3
	v_exp_f32_e32 v1, v1
	v_mul_f32_e32 v2, v38, v3
	v_fmamk_f32 v0, v0, 0x3b808081, v193
	v_rcp_f32_e32 v0, v0
	v_fmamk_f32 v1, v1, 0x3b808081, v193
	v_rcp_f32_e32 v1, v1
	v_exp_f32_e32 v2, v2
	v_cvt_pk_u8_f32 v0, v0, 0, 0
	v_mul_f32_e32 v4, v40, v3
	v_cvt_pk_u8_f32 v0, v1, 1, v0
	v_fmamk_f32 v1, v2, 0x3b808081, v193
	v_mul_f32_e32 v2, v39, v3
	v_exp_f32_e32 v4, v4
	v_exp_f32_e32 v2, v2
	v_rcp_f32_e32 v1, v1
	v_mul_f32_e32 v5, v41, v3
	v_fmamk_f32 v4, v4, 0x3b808081, v193
	v_fmamk_f32 v2, v2, 0x3b808081, v193
	v_rcp_f32_e32 v4, v4
	v_rcp_f32_e32 v2, v2
	v_exp_f32_e32 v5, v5
	v_cvt_pk_u8_f32 v0, v1, 2, v0
	v_cvt_pk_u8_f32 v1, v4, 0, 0
	v_mul_f32_e32 v4, v42, v3
	v_cvt_pk_u8_f32 v0, v2, 3, v0
	v_fmamk_f32 v2, v5, 0x3b808081, v193
	v_exp_f32_e32 v4, v4
	v_mul_f32_e32 v5, v43, v3
	v_exp_f32_e32 v5, v5
	v_rcp_f32_e32 v2, v2
	v_fmamk_f32 v4, v4, 0x3b808081, v193
	v_rcp_f32_e32 v4, v4
	v_fmamk_f32 v5, v5, 0x3b808081, v193
	v_rcp_f32_e32 v5, v5
	v_mul_f32_e32 v6, v44, v3
	v_cvt_pk_u8_f32 v1, v2, 1, v1
	v_exp_f32_e32 v6, v6
	v_cvt_pk_u8_f32 v1, v4, 2, v1
	v_mul_f32_e32 v4, v45, v3
	v_cvt_pk_u8_f32 v1, v5, 3, v1
	v_exp_f32_e32 v4, v4
	v_mul_f32_e32 v5, v46, v3
	v_exp_f32_e32 v5, v5
	v_fmamk_f32 v2, v6, 0x3b808081, v193
	v_rcp_f32_e32 v2, v2
	v_fmamk_f32 v4, v4, 0x3b808081, v193
	v_rcp_f32_e32 v4, v4
	v_fmamk_f32 v5, v5, 0x3b808081, v193
	v_mul_f32_e32 v6, v47, v3
	v_rcp_f32_e32 v5, v5
	v_exp_f32_e32 v6, v6
	v_cvt_pk_u8_f32 v2, v2, 0, 0
	v_cvt_pk_u8_f32 v2, v4, 1, v2
	v_cvt_pk_u8_f32 v2, v5, 2, v2
	v_fmamk_f32 v4, v6, 0x3b808081, v193
	v_mul_f32_e32 v5, v32, v3
	v_mul_f32_e32 v6, v33, v3
	v_rcp_f32_e32 v4, v4
	v_exp_f32_e32 v5, v5
	v_exp_f32_e32 v6, v6
	v_cvt_pk_u8_f32 v2, v4, 3, v2
	v_fmamk_f32 v4, v5, 0x3b808081, v193
	v_fmamk_f32 v5, v6, 0x3b808081, v193
	v_mul_f32_e32 v6, v34, v3
	v_exp_f32_e32 v6, v6
	v_mul_f32_e32 v3, v35, v3
	v_exp_f32_e32 v3, v3
	v_rcp_f32_e32 v4, v4
	v_rcp_f32_e32 v5, v5
	v_fmamk_f32 v6, v6, 0x3b808081, v193
	v_rcp_f32_e32 v6, v6
	v_fmamk_f32 v3, v3, 0x3b808081, v193
	v_rcp_f32_e32 v3, v3
	v_cvt_pk_u8_f32 v4, v4, 0, 0
	v_cvt_pk_u8_f32 v4, v5, 1, v4
	v_cvt_pk_u8_f32 v4, v6, 2, v4
	v_cvt_pk_u8_f32 v3, v3, 3, v4
	v_lshlrev_b64 v[4:5], 10, v[48:49]
	v_lshl_add_u64 v[4:5], v[178:179], 0, v[4:5]
	global_store_dwordx4 v[4:5], v[0:3], off

.LBB0_622:
	s_andn2_b64 vcc, exec, s[4:5]
	s_cbranch_vccnz .LBB0_629
	s_and_b64 vcc, exec, s[10:11]
	s_cbranch_vccnz .LBB0_639
	v_mul_f32_e32 v4, v37, v37
	v_fmac_f32_e32 v4, v36, v36
	v_fmac_f32_e32 v4, v38, v38
	v_fmac_f32_e32 v4, v39, v39
	v_fmac_f32_e32 v4, v40, v40
	v_fmac_f32_e32 v4, v41, v41
	v_fmac_f32_e32 v4, v42, v42
	v_fmac_f32_e32 v4, v43, v43
	v_pk_mul_f32 v[2:3], v[44:45], v[44:45]
	v_pk_mul_f32 v[0:1], v[46:47], v[46:47]
	v_add_f32_e32 v2, v2, v4
	v_add_f32_e32 v2, v3, v2
	v_add_f32_e32 v0, v0, v2
	v_add_f32_e32 v4, v1, v0
	v_pk_mul_f32 v[2:3], v[32:33], v[32:33]
	v_pk_mul_f32 v[0:1], v[34:35], v[34:35]
	v_add_f32_e32 v2, v2, v4
	v_add_f32_e32 v2, v3, v2
	v_add_f32_e32 v0, v0, v2
	v_and_b32_e32 v2, 64, v195
	v_add_f32_e32 v0, v1, v0
	v_xor_b32_e32 v1, 16, v195
	v_add_u32_e32 v2, 64, v2
	v_cmp_lt_i32_e32 vcc, v1, v2
	s_nop 1
	v_cndmask_b32_e32 v1, v195, v1, vcc
	v_lshlrev_b32_e32 v1, 2, v1
	ds_bpermute_b32 v1, v1, v0
	s_waitcnt lgkmcnt(0)
	v_add_f32_e32 v0, v0, v1
	v_xor_b32_e32 v1, 32, v195
	v_cmp_lt_i32_e32 vcc, v1, v2
	s_nop 1
	v_cndmask_b32_e32 v1, v195, v1, vcc
	v_lshlrev_b32_e32 v1, 2, v1
	ds_bpermute_b32 v1, v1, v0
	s_waitcnt lgkmcnt(0)
	v_add_f32_e32 v0, v0, v1
	v_mul_f32_e32 v1, v16, v16
	v_mul_f32_e32 v0, v1, v0
	v_fmamk_f32 v0, v0, 0x3c800000, v194
	v_mul_f32_e32 v1, 0x4b800000, v0
	v_cmp_gt_f32_e32 vcc, s42, v0
	s_nop 1
	v_cndmask_b32_e32 v0, v0, v1, vcc
	v_rsq_f32_e32 v0, v0
	s_nop 0
	v_mul_f32_e32 v1, 0x45800000, v0
	v_cndmask_b32_e32 v0, v0, v1, vcc
	v_mul_f32_e32 v0, v16, v0
	v_pk_mul_f32 v[18:19], v[36:37], v[0:1] op_sel_hi:[1,0]
	v_pk_mul_f32 v[2:3], v[38:39], v[0:1] op_sel_hi:[1,0]
	v_pk_mul_f32 v[4:5], v[40:41], v[0:1] op_sel_hi:[1,0]
	v_pk_mul_f32 v[6:7], v[42:43], v[0:1] op_sel_hi:[1,0]
	v_pk_mul_f32 v[8:9], v[44:45], v[0:1] op_sel_hi:[1,0]
	v_pk_mul_f32 v[10:11], v[46:47], v[0:1] op_sel_hi:[1,0]
	v_pk_mul_f32 v[12:13], v[32:33], v[0:1] op_sel_hi:[1,0]
	v_pk_mul_f32 v[0:1], v[34:35], v[0:1] op_sel_hi:[1,0]
	v_pk_mul_f32 v[12:13], v[174:175], v[12:13]
	v_pk_mul_f32 v[14:15], v[176:177], v[0:1]
	v_pk_mul_f32 v[10:11], v[172:173], v[10:11]
	v_pk_mul_f32 v[8:9], v[170:171], v[8:9]
	v_pk_mul_f32 v[6:7], v[168:169], v[6:7]
	v_pk_mul_f32 v[4:5], v[166:167], v[4:5]
	v_pk_mul_f32 v[2:3], v[164:165], v[2:3]
	v_pk_mul_f32 v[0:1], v[162:163], v[18:19]
	s_cbranch_execnz .LBB0_626
.LBB0_625:
	v_pk_mul_f32 v[14:15], v[34:35], v[16:17] op_sel_hi:[1,0]
	v_pk_mul_f32 v[10:11], v[46:47], v[16:17] op_sel_hi:[1,0]
	v_pk_mul_f32 v[6:7], v[42:43], v[16:17] op_sel_hi:[1,0]
	v_pk_mul_f32 v[2:3], v[38:39], v[16:17] op_sel_hi:[1,0]
	v_pk_mul_f32 v[12:13], v[32:33], v[16:17] op_sel_hi:[1,0]
	v_pk_mul_f32 v[8:9], v[44:45], v[16:17] op_sel_hi:[1,0]
	v_pk_mul_f32 v[4:5], v[40:41], v[16:17] op_sel_hi:[1,0]
	v_pk_mul_f32 v[0:1], v[36:37], v[16:17] op_sel_hi:[1,0]
.LBB0_626:
	s_and_saveexec_b64 s[4:5], s[70:71]
	s_cbranch_execz .LBB0_628
	s_waitcnt vmcnt(2)
	v_pk_mul_f32 v[24:25], v[8:9], v[204:205]
	v_pk_mul_f32 v[26:27], v[0:1], v[204:205]
	v_pk_mul_f32 v[36:37], v[10:11], v[206:207]
	v_pk_mul_f32 v[38:39], v[2:3], v[206:207]
	v_pk_mul_f32 v[46:47], v[14:15], v[210:211]
	v_mul_f32_e32 v44, v6, v210
	v_mov_b32_e32 v210, v215
	v_pk_fma_f32 v[204:205], v[0:1], v[200:201], v[24:25] neg_lo:[0,0,1] neg_hi:[0,0,1]
	v_pk_fma_f32 v[24:25], v[8:9], v[200:201], v[26:27]
	v_pk_fma_f32 v[206:207], v[2:3], v[202:203], v[36:37] neg_lo:[0,0,1] neg_hi:[0,0,1]
	v_pk_fma_f32 v[26:27], v[10:11], v[202:203], v[38:39]
	v_pk_fma_f32 v[202:203], v[6:7], v[214:215], v[46:47] neg_lo:[0,0,1] neg_hi:[0,0,1]
	v_mov_b32_e32 v6, v15
	v_pk_mul_f32 v[0:1], v[6:7], v[210:211]
	v_pk_mul_f32 v[40:41], v[12:13], v[208:209]
	v_pk_mul_f32 v[208:209], v[4:5], v[208:209]
	v_mul_f32_e32 v42, v14, v214
	v_mov_b32_e32 v43, v0
	v_mov_b32_e32 v45, v1
	v_pk_fma_f32 v[200:201], v[4:5], v[212:213], v[40:41] neg_lo:[0,0,1] neg_hi:[0,0,1]
	v_pk_fma_f32 v[208:209], v[12:13], v[212:213], v[208:209]
	v_pk_add_f32 v[210:211], v[42:43], v[44:45]
	s_nop 0
	v_mov_b64_e32 v[0:1], v[204:205]
	v_mov_b64_e32 v[2:3], v[206:207]
	v_mov_b64_e32 v[4:5], v[200:201]
	v_mov_b64_e32 v[6:7], v[202:203]
	v_mov_b64_e32 v[8:9], v[24:25]
	v_mov_b64_e32 v[10:11], v[26:27]
	v_mov_b64_e32 v[12:13], v[208:209]
	v_mov_b64_e32 v[14:15], v[210:211]
.LBB0_628:
	s_or_b64 exec, exec, s[4:5]
	v_lshlrev_b32_e32 v16, 7, v48
	v_and_b32_e32 v150, 0x3ff80, v16
	v_lshl_add_u64 v[16:17], v[96:97], 0, v[150:151]
	v_cvt_pk_bf16_f32 v0, v0, v1
	v_cvt_pk_bf16_f32 v1, v2, v3
	v_cvt_pk_bf16_f32 v2, v4, v5
	v_cvt_pk_bf16_f32 v3, v6, v7
	v_cvt_pk_bf16_f32 v4, v8, v9
	v_cvt_pk_bf16_f32 v5, v10, v11
	v_cvt_pk_bf16_f32 v6, v12, v13
	v_cvt_pk_bf16_f32 v7, v14, v15
	global_store_dwordx4 v[16:17], v[0:3], off
	global_store_dwordx4 v[16:17], v[4:7], off offset:16
